# all end-of-epilogue store drains removed (stores drain under the next unit's K-loop counted waits); fast-latent norm loop with coefficients in registers
# speedup vs baseline: 1.0211x; 1.0104x over previous
; __device__ __forceinline__ float bf_lo(unsigned u) { return __uint_as_float(u << 16); }
; __device__ __forceinline__ float bf_hi(unsigned u) { return __uint_as_float(u & 0xffff0000u); }
; __device__ __forceinline__ u32x4 pack8(const f32x4 a, const f32x4 b) { u32x4 w; w.x = cvt_pk_bf16(a[0], a[1]); w.y = cvt_pk_bf16(a[2], a[3]); w.z = cvt_pk_bf16(b[0], b[1]); w.w = cvt_pk_bf16(b[2], b[3]); return w; }
;     __device__ __forceinline__ bool operator()(f32x4 (&acc)[2][2][4][2], const Unit& u, int wr, int wc, int fr, int fq) const {
;     ...
;         const int vec = u.pm >> 5;
;         const int row0 = u.pm * 256 + wr * 64 + fr, c0 = u.pn * 256 + wc * 32 + fq * 8;
;         const float* gp = gate + vec * 12288 + c0;
;         f32x4 gv[2][2];
; #pragma unroll
;         for (int bj = 0; bj < 2; ++bj) { gv[bj][0] = *(const f32x4*)(gp + bj * 128); gv[bj][1] = *(const f32x4*)(gp + bj * 128 + 4); }
; #pragma unroll
;         for (int b4 = 0; b4 < 4; ++b4) {
;             const int ai = b4 >> 1, mh = (b4 & 1) * 2;
;             u32x4 xq[2][2];
; #pragma unroll
;             for (int mm = 0; mm < 2; ++mm)
; #pragma unroll
;                 for (int bj = 0; bj < 2; ++bj) xq[mm][bj] = *(const u32x4*)(xb + (size_t)(row0 + ai * 128 + (mh + mm) * 16) * D + c0 + bj * 128);
;             __builtin_amdgcn_sched_barrier(0);
; #pragma unroll
;             for (int mm = 0; mm < 2; ++mm)
; #pragma unroll
;                 for (int bj = 0; bj < 2; ++bj)
;                 { const u32x4 q = xq[mm][bj]; const f32x4 x0 = (f32x4){bf_lo(q.x), bf_hi(q.x), bf_lo(q.y), bf_hi(q.y)}, x1 = (f32x4){bf_lo(q.z), bf_hi(q.z), bf_lo(q.w), bf_hi(q.w)};
;                     *(u32x4*)(xb + (size_t)(row0 + ai * 128 + (mh + mm) * 16) * D + c0 + bj * 128) = pack8(x0 + gv[bj][0] * acc[ai][bj][mh + mm][0], x1 + gv[bj][1] * acc[ai][bj][mh + mm][1]); }
;             __builtin_amdgcn_sched_barrier(0);
;         }
.LBB0_48:
	s_lshr_b32 s14, s86, 5
	s_mulk_i32 s14, 0x3000
	s_ashr_i32 s15, s14, 31
	s_lshl_b64 s[14:15], s[14:15], 2
	v_lshl_or_b32 v154, s87, 8, v169
	s_add_u32 s14, s21, s14
	s_addc_u32 s15, s34, s15
	v_ashrrev_i32_e32 v155, 31, v154
	v_lshl_add_u32 v174, s86, 8, v160
	v_lshl_add_u64 v[132:133], v[154:155], 2, s[14:15]
	v_lshlrev_b64 v[154:155], 1, v[154:155]
	v_ashrrev_i32_e32 v175, 31, v174
	v_lshl_add_u64 v[156:157], s[6:7], 0, v[154:155]
	v_lshlrev_b64 v[158:159], 12, v[174:175]
	v_lshl_add_u64 v[178:179], v[156:157], 0, v[158:159]
	global_load_dwordx4 v[136:139], v[132:133], off offset:16
	global_load_dwordx4 v[140:143], v[132:133], off
	global_load_dwordx4 v[128:131], v[132:133], off offset:528
	s_nop 0
	global_load_dwordx4 v[132:135], v[132:133], off offset:512
	s_nop 0
	global_load_dwordx4 v[170:173], v[178:179], off
	global_load_dwordx4 v[182:185], v[178:179], off offset:256
	v_or_b32_e32 v178, 16, v174
	v_ashrrev_i32_e32 v179, 31, v178
	v_lshlrev_b64 v[178:179], 12, v[178:179]
	v_lshl_add_u64 v[180:181], v[156:157], 0, v[178:179]
	global_load_dwordx4 v[190:193], v[180:181], off
	global_load_dwordx4 v[194:197], v[180:181], off offset:256
	v_or_b32_e32 v200, 32, v174
	v_or_b32_e32 v208, 48, v174
	v_ashrrev_i32_e32 v201, 31, v200
	v_ashrrev_i32_e32 v209, 31, v208
	v_lshlrev_b64 v[226:227], 12, v[200:201]
	v_lshlrev_b64 v[228:229], 12, v[208:209]
	v_lshl_add_u64 v[204:205], v[156:157], 0, v[226:227]
	v_lshl_add_u64 v[222:223], v[156:157], 0, v[228:229]
	global_load_dwordx4 v[200:203], v[204:205], off
	s_nop 0
	global_load_dwordx4 v[204:207], v[204:205], off offset:256
	s_nop 0
	global_load_dwordx4 v[208:211], v[222:223], off
	s_nop 0
	global_load_dwordx4 v[222:225], v[222:223], off offset:256
	s_waitcnt vmcnt(4)
	v_lshlrev_b32_e32 v180, 16, v170
	v_and_b32_e32 v181, 0xffff0000, v170
	v_lshlrev_b32_e32 v170, 16, v171
	v_and_b32_e32 v171, 0xffff0000, v171
	v_lshlrev_b32_e32 v198, 16, v172
	v_and_b32_e32 v199, 0xffff0000, v172
	v_lshlrev_b32_e32 v172, 16, v173
	v_and_b32_e32 v173, 0xffff0000, v173
	v_pk_fma_f32 v[124:125], v[124:125], v[140:141], v[180:181]
	v_pk_fma_f32 v[126:127], v[126:127], v[142:143], v[170:171]
	v_pk_fma_f32 v[170:171], v[122:123], v[138:139], v[172:173]
	v_pk_fma_f32 v[122:123], v[120:121], v[136:137], v[198:199]
	v_cvt_pk_bf16_f32 v120, v124, v125
	v_lshl_add_u64 v[124:125], s[6:7], 0, v[158:159]
	v_cvt_pk_bf16_f32 v121, v126, v127
	v_cvt_pk_bf16_f32 v122, v122, v123
	v_cvt_pk_bf16_f32 v123, v170, v171
	v_lshl_add_u64 v[124:125], v[124:125], 0, v[154:155]
	global_store_dwordx4 v[124:125], v[120:123], off
	v_lshlrev_b32_e32 v126, 16, v184
	v_and_b32_e32 v127, 0xffff0000, v184
	v_lshlrev_b32_e32 v120, 16, v182
	v_and_b32_e32 v121, 0xffff0000, v182
	v_lshlrev_b32_e32 v122, 16, v183
	v_and_b32_e32 v123, 0xffff0000, v183
	v_lshlrev_b32_e32 v170, 16, v185
	v_and_b32_e32 v171, 0xffff0000, v185
	v_pk_fma_f32 v[118:119], v[118:119], v[134:135], v[122:123]
	v_pk_fma_f32 v[116:117], v[116:117], v[132:133], v[120:121]
	v_pk_fma_f32 v[120:121], v[114:115], v[130:131], v[170:171]
	v_pk_fma_f32 v[114:115], v[112:113], v[128:129], v[126:127]
	v_cvt_pk_bf16_f32 v112, v116, v117
	v_cvt_pk_bf16_f32 v113, v118, v119
	v_lshlrev_b32_e32 v116, 16, v192
	v_cvt_pk_bf16_f32 v114, v114, v115
	v_cvt_pk_bf16_f32 v115, v120, v121
	global_store_dwordx4 v[124:125], v[112:115], off offset:256
	v_and_b32_e32 v117, 0xffff0000, v192
	v_lshlrev_b32_e32 v118, 16, v193
	v_lshlrev_b32_e32 v112, 16, v190
	v_and_b32_e32 v113, 0xffff0000, v190
	v_and_b32_e32 v119, 0xffff0000, v193
	v_pk_fma_f32 v[108:109], v[108:109], v[140:141], v[112:113]
	v_lshlrev_b32_e32 v114, 16, v191
	v_and_b32_e32 v115, 0xffff0000, v191
	v_pk_fma_f32 v[112:113], v[106:107], v[138:139], v[118:119]
	v_pk_fma_f32 v[106:107], v[104:105], v[136:137], v[116:117]
	v_cvt_pk_bf16_f32 v104, v108, v109
	v_lshl_add_u64 v[108:109], s[6:7], 0, v[178:179]
	v_pk_fma_f32 v[110:111], v[110:111], v[142:143], v[114:115]
	v_lshl_add_u64 v[108:109], v[108:109], 0, v[154:155]
	v_cvt_pk_bf16_f32 v105, v110, v111
	v_cvt_pk_bf16_f32 v106, v106, v107
	v_cvt_pk_bf16_f32 v107, v112, v113
	global_store_dwordx4 v[108:109], v[104:107], off
	v_lshlrev_b32_e32 v110, 16, v196
	v_and_b32_e32 v111, 0xffff0000, v196
	v_lshlrev_b32_e32 v104, 16, v194
	v_and_b32_e32 v105, 0xffff0000, v194
	v_lshlrev_b32_e32 v112, 16, v197
	v_and_b32_e32 v113, 0xffff0000, v197
	v_lshlrev_b32_e32 v106, 16, v195
	v_and_b32_e32 v107, 0xffff0000, v195
	v_pk_fma_f32 v[100:101], v[100:101], v[132:133], v[104:105]
	v_pk_fma_f32 v[104:105], v[98:99], v[130:131], v[112:113]
	v_pk_fma_f32 v[98:99], v[96:97], v[128:129], v[110:111]
	v_pk_fma_f32 v[102:103], v[102:103], v[134:135], v[106:107]
	v_cvt_pk_bf16_f32 v96, v100, v101
	s_nop 0
	v_cvt_pk_bf16_f32 v97, v102, v103
	v_cvt_pk_bf16_f32 v98, v98, v99
	v_cvt_pk_bf16_f32 v99, v104, v105
	global_store_dwordx4 v[108:109], v[96:99], off offset:256
	v_lshl_add_u64 v[242:243], v[158:159], 0, s[54:55]
	v_lshl_add_u64 v[250:251], v[158:159], 0, s[56:57]
	v_lshl_add_u64 v[234:235], v[156:157], 0, v[242:243]
	v_lshl_add_u64 v[246:247], v[156:157], 0, v[250:251]
	global_load_dwordx4 v[230:233], v[234:235], off
	s_nop 0
	global_load_dwordx4 v[234:237], v[234:235], off offset:256
	s_nop 0
	global_load_dwordx4 v[238:241], v[246:247], off
	s_nop 0
	global_load_dwordx4 v[246:249], v[246:247], off offset:256
	s_waitcnt vmcnt(8)
; __device__ __forceinline__ float bf_lo(unsigned u) { return __uint_as_float(u << 16); }
; __device__ __forceinline__ float bf_hi(unsigned u) { return __uint_as_float(u & 0xffff0000u); }
; __device__ __forceinline__ u32x4 pack8(const f32x4 a, const f32x4 b) { u32x4 w; w.x = cvt_pk_bf16(a[0], a[1]); w.y = cvt_pk_bf16(a[2], a[3]); w.z = cvt_pk_bf16(b[0], b[1]); w.w = cvt_pk_bf16(b[2], b[3]); return w; }
;     __device__ __forceinline__ bool operator()(f32x4 (&acc)[2][2][4][2], const Unit& u, int wr, int wc, int fr, int fq) const {
;     ...
; #pragma unroll
;             for (int mm = 0; mm < 2; ++mm)
; #pragma unroll
;                 for (int bj = 0; bj < 2; ++bj)
;                 { const u32x4 q = xq[mm][bj]; const f32x4 x0 = (f32x4){bf_lo(q.x), bf_hi(q.x), bf_lo(q.y), bf_hi(q.y)}, x1 = (f32x4){bf_lo(q.z), bf_hi(q.z), bf_lo(q.w), bf_hi(q.w)};
;                     *(u32x4*)(xb + (size_t)(row0 + ai * 128 + (mh + mm) * 16) * D + c0 + bj * 128) = pack8(x0 + gv[bj][0] * acc[ai][bj][mh + mm][0], x1 + gv[bj][1] * acc[ai][bj][mh + mm][1]); }
;             __builtin_amdgcn_sched_barrier(0);
	v_lshlrev_b32_e32 v116, 16, v200
	v_and_b32_e32 v117, 0xffff0000, v200
	v_lshlrev_b32_e32 v200, 16, v201
	v_and_b32_e32 v201, 0xffff0000, v201
	v_lshlrev_b32_e32 v118, 16, v202
	v_and_b32_e32 v119, 0xffff0000, v202
	v_lshlrev_b32_e32 v202, 16, v203
	v_and_b32_e32 v203, 0xffff0000, v203
	v_pk_fma_f32 v[92:93], v[92:93], v[140:141], v[116:117]
	v_pk_fma_f32 v[94:95], v[94:95], v[142:143], v[200:201]
	v_pk_fma_f32 v[200:201], v[90:91], v[138:139], v[202:203]
	v_pk_fma_f32 v[90:91], v[88:89], v[136:137], v[118:119]
	v_cvt_pk_bf16_f32 v88, v92, v93
	v_lshl_add_u64 v[92:93], s[6:7], 0, v[226:227]
	v_cvt_pk_bf16_f32 v89, v94, v95
	v_cvt_pk_bf16_f32 v90, v90, v91
	v_cvt_pk_bf16_f32 v91, v200, v201
	v_lshl_add_u64 v[92:93], v[92:93], 0, v[154:155]
	global_store_dwordx4 v[92:93], v[88:91], off
	v_lshlrev_b32_e32 v94, 16, v206
	v_and_b32_e32 v95, 0xffff0000, v206
	v_lshlrev_b32_e32 v88, 16, v204
	v_and_b32_e32 v89, 0xffff0000, v204
	v_lshlrev_b32_e32 v90, 16, v205
	v_and_b32_e32 v91, 0xffff0000, v205
	v_lshlrev_b32_e32 v200, 16, v207
	v_and_b32_e32 v201, 0xffff0000, v207
	v_pk_fma_f32 v[86:87], v[86:87], v[134:135], v[90:91]
	v_pk_fma_f32 v[84:85], v[84:85], v[132:133], v[88:89]
	v_pk_fma_f32 v[88:89], v[82:83], v[130:131], v[200:201]
	v_pk_fma_f32 v[82:83], v[80:81], v[128:129], v[94:95]
	v_cvt_pk_bf16_f32 v80, v84, v85
	v_cvt_pk_bf16_f32 v81, v86, v87
	v_lshlrev_b32_e32 v84, 16, v210
	v_cvt_pk_bf16_f32 v82, v82, v83
	v_cvt_pk_bf16_f32 v83, v88, v89
	global_store_dwordx4 v[92:93], v[80:83], off offset:256
	v_and_b32_e32 v85, 0xffff0000, v210
	v_lshlrev_b32_e32 v86, 16, v211
	v_lshlrev_b32_e32 v80, 16, v208
	v_and_b32_e32 v81, 0xffff0000, v208
	v_and_b32_e32 v87, 0xffff0000, v211
	v_pk_fma_f32 v[76:77], v[76:77], v[140:141], v[80:81]
	v_lshlrev_b32_e32 v82, 16, v209
	v_and_b32_e32 v83, 0xffff0000, v209
	v_pk_fma_f32 v[80:81], v[74:75], v[138:139], v[86:87]
	v_pk_fma_f32 v[74:75], v[72:73], v[136:137], v[84:85]
	v_cvt_pk_bf16_f32 v72, v76, v77
	v_lshl_add_u64 v[76:77], s[6:7], 0, v[228:229]
	v_pk_fma_f32 v[78:79], v[78:79], v[142:143], v[82:83]
	v_lshl_add_u64 v[76:77], v[76:77], 0, v[154:155]
	v_cvt_pk_bf16_f32 v73, v78, v79
	v_cvt_pk_bf16_f32 v74, v74, v75
	v_cvt_pk_bf16_f32 v75, v80, v81
	global_store_dwordx4 v[76:77], v[72:75], off
	v_lshlrev_b32_e32 v78, 16, v224
	v_and_b32_e32 v79, 0xffff0000, v224
	v_lshlrev_b32_e32 v72, 16, v222
	v_and_b32_e32 v73, 0xffff0000, v222
	v_lshlrev_b32_e32 v80, 16, v225
	v_and_b32_e32 v81, 0xffff0000, v225
	v_lshlrev_b32_e32 v74, 16, v223
	v_and_b32_e32 v75, 0xffff0000, v223
	v_pk_fma_f32 v[68:69], v[68:69], v[132:133], v[72:73]
	v_pk_fma_f32 v[72:73], v[66:67], v[130:131], v[80:81]
	v_pk_fma_f32 v[66:67], v[64:65], v[128:129], v[78:79]
	v_pk_fma_f32 v[70:71], v[70:71], v[134:135], v[74:75]
	v_cvt_pk_bf16_f32 v64, v68, v69
	s_nop 0
	v_cvt_pk_bf16_f32 v65, v70, v71
	v_cvt_pk_bf16_f32 v66, v66, v67
	v_cvt_pk_bf16_f32 v67, v72, v73
	global_store_dwordx4 v[76:77], v[64:67], off offset:256
	s_mov_b64 s[14:15], 0xb0000
	v_lshl_add_u64 v[226:227], v[158:159], 0, s[58:59]
	v_lshl_add_u64 v[228:229], v[158:159], 0, s[14:15]
	v_lshl_add_u64 v[204:205], v[156:157], 0, v[226:227]
	v_lshl_add_u64 v[222:223], v[156:157], 0, v[228:229]
	global_load_dwordx4 v[200:203], v[204:205], off
	s_nop 0
	global_load_dwordx4 v[204:207], v[204:205], off offset:256
	s_nop 0
	global_load_dwordx4 v[208:211], v[222:223], off
	s_nop 0
	global_load_dwordx4 v[222:225], v[222:223], off offset:256
	s_waitcnt vmcnt(8)
; __device__ __forceinline__ float bf_lo(unsigned u) { return __uint_as_float(u << 16); }
; __device__ __forceinline__ float bf_hi(unsigned u) { return __uint_as_float(u & 0xffff0000u); }
; __device__ __forceinline__ u32x4 pack8(const f32x4 a, const f32x4 b) { u32x4 w; w.x = cvt_pk_bf16(a[0], a[1]); w.y = cvt_pk_bf16(a[2], a[3]); w.z = cvt_pk_bf16(b[0], b[1]); w.w = cvt_pk_bf16(b[2], b[3]); return w; }
; template <int NT, class Epi>
; __device__ __forceinline__ void gemm_phase(LAS unsigned char* lds, const int K, const Sched& S, const Epi& E, const int wave_s) {
;     ...
;         const bool keep = E(acc, cur, wr, wc, fr, fq);
;         __builtin_amdgcn_s_waitcnt(0x0F70);
;         if (!has_next) break;
;     __device__ __forceinline__ bool operator()(f32x4 (&acc)[2][2][4][2], const Unit& u, int wr, int wc, int fr, int fq) const {
;     ...
;         for (int b4 = 0; b4 < 4; ++b4) {
;             const int ai = b4 >> 1, mh = (b4 & 1) * 2;
;             u32x4 xq[2][2];
; #pragma unroll
;             for (int mm = 0; mm < 2; ++mm)
; #pragma unroll
;                 for (int bj = 0; bj < 2; ++bj) xq[mm][bj] = *(const u32x4*)(xb + (size_t)(row0 + ai * 128 + (mh + mm) * 16) * D + c0 + bj * 128);
;             __builtin_amdgcn_sched_barrier(0);
; #pragma unroll
;             for (int mm = 0; mm < 2; ++mm)
; #pragma unroll
;                 for (int bj = 0; bj < 2; ++bj)
;                 { const u32x4 q = xq[mm][bj]; const f32x4 x0 = (f32x4){bf_lo(q.x), bf_hi(q.x), bf_lo(q.y), bf_hi(q.y)}, x1 = (f32x4){bf_lo(q.z), bf_hi(q.z), bf_lo(q.w), bf_hi(q.w)};
;                     *(u32x4*)(xb + (size_t)(row0 + ai * 128 + (mh + mm) * 16) * D + c0 + bj * 128) = pack8(x0 + gv[bj][0] * acc[ai][bj][mh + mm][0], x1 + gv[bj][1] * acc[ai][bj][mh + mm][1]); }
;             __builtin_amdgcn_sched_barrier(0);
;         }
	v_lshlrev_b32_e32 v84, 16, v230
	v_and_b32_e32 v85, 0xffff0000, v230
	v_lshlrev_b32_e32 v230, 16, v231
	v_and_b32_e32 v231, 0xffff0000, v231
	v_lshlrev_b32_e32 v86, 16, v232
	v_and_b32_e32 v87, 0xffff0000, v232
	v_lshlrev_b32_e32 v232, 16, v233
	v_and_b32_e32 v233, 0xffff0000, v233
	v_pk_fma_f32 v[60:61], v[60:61], v[140:141], v[84:85]
	v_pk_fma_f32 v[62:63], v[62:63], v[142:143], v[230:231]
	v_pk_fma_f32 v[230:231], v[58:59], v[138:139], v[232:233]
	v_pk_fma_f32 v[58:59], v[56:57], v[136:137], v[86:87]
	v_cvt_pk_bf16_f32 v56, v60, v61
	v_lshl_add_u64 v[60:61], s[6:7], 0, v[242:243]
	v_cvt_pk_bf16_f32 v57, v62, v63
	v_cvt_pk_bf16_f32 v58, v58, v59
	v_cvt_pk_bf16_f32 v59, v230, v231
	v_lshl_add_u64 v[60:61], v[60:61], 0, v[154:155]
	global_store_dwordx4 v[60:61], v[56:59], off
	v_lshlrev_b32_e32 v62, 16, v236
	v_and_b32_e32 v63, 0xffff0000, v236
	v_lshlrev_b32_e32 v56, 16, v234
	v_and_b32_e32 v57, 0xffff0000, v234
	v_lshlrev_b32_e32 v58, 16, v235
	v_and_b32_e32 v59, 0xffff0000, v235
	v_lshlrev_b32_e32 v230, 16, v237
	v_and_b32_e32 v231, 0xffff0000, v237
	v_pk_fma_f32 v[54:55], v[54:55], v[134:135], v[58:59]
	v_pk_fma_f32 v[52:53], v[52:53], v[132:133], v[56:57]
	v_pk_fma_f32 v[56:57], v[50:51], v[130:131], v[230:231]
	v_pk_fma_f32 v[50:51], v[48:49], v[128:129], v[62:63]
	v_cvt_pk_bf16_f32 v48, v52, v53
	v_cvt_pk_bf16_f32 v49, v54, v55
	v_lshlrev_b32_e32 v52, 16, v240
	v_cvt_pk_bf16_f32 v50, v50, v51
	v_cvt_pk_bf16_f32 v51, v56, v57
	global_store_dwordx4 v[60:61], v[48:51], off offset:256
	v_and_b32_e32 v53, 0xffff0000, v240
	v_lshlrev_b32_e32 v54, 16, v241
	v_lshlrev_b32_e32 v48, 16, v238
	v_and_b32_e32 v49, 0xffff0000, v238
	v_and_b32_e32 v55, 0xffff0000, v241
	v_pk_fma_f32 v[44:45], v[44:45], v[140:141], v[48:49]
	v_lshlrev_b32_e32 v50, 16, v239
	v_and_b32_e32 v51, 0xffff0000, v239
	v_pk_fma_f32 v[48:49], v[42:43], v[138:139], v[54:55]
	v_pk_fma_f32 v[42:43], v[40:41], v[136:137], v[52:53]
	v_cvt_pk_bf16_f32 v40, v44, v45
	v_lshl_add_u64 v[44:45], s[6:7], 0, v[250:251]
	v_pk_fma_f32 v[46:47], v[46:47], v[142:143], v[50:51]
	v_lshl_add_u64 v[44:45], v[44:45], 0, v[154:155]
	v_cvt_pk_bf16_f32 v41, v46, v47
	v_cvt_pk_bf16_f32 v42, v42, v43
	v_cvt_pk_bf16_f32 v43, v48, v49
	global_store_dwordx4 v[44:45], v[40:43], off
	v_lshlrev_b32_e32 v46, 16, v248
	v_and_b32_e32 v47, 0xffff0000, v248
	v_lshlrev_b32_e32 v40, 16, v246
	v_and_b32_e32 v41, 0xffff0000, v246
	v_lshlrev_b32_e32 v48, 16, v249
	v_and_b32_e32 v49, 0xffff0000, v249
	v_lshlrev_b32_e32 v42, 16, v247
	v_and_b32_e32 v43, 0xffff0000, v247
	v_pk_fma_f32 v[36:37], v[36:37], v[132:133], v[40:41]
	v_pk_fma_f32 v[40:41], v[34:35], v[130:131], v[48:49]
	v_pk_fma_f32 v[34:35], v[32:33], v[128:129], v[46:47]
	v_pk_fma_f32 v[38:39], v[38:39], v[134:135], v[42:43]
	v_cvt_pk_bf16_f32 v32, v36, v37
	s_nop 0
	v_cvt_pk_bf16_f32 v33, v38, v39
	v_cvt_pk_bf16_f32 v34, v34, v35
	v_cvt_pk_bf16_f32 v35, v40, v41
	global_store_dwordx4 v[44:45], v[32:35], off offset:256
	s_waitcnt vmcnt(4)
	v_lshlrev_b32_e32 v52, 16, v200
	v_and_b32_e32 v53, 0xffff0000, v200
	v_lshlrev_b32_e32 v200, 16, v201
	v_and_b32_e32 v201, 0xffff0000, v201
	v_lshlrev_b32_e32 v54, 16, v202
	v_and_b32_e32 v55, 0xffff0000, v202
	v_lshlrev_b32_e32 v202, 16, v203
	v_and_b32_e32 v203, 0xffff0000, v203
	v_pk_fma_f32 v[28:29], v[28:29], v[140:141], v[52:53]
	v_pk_fma_f32 v[30:31], v[30:31], v[142:143], v[200:201]
	v_pk_fma_f32 v[200:201], v[26:27], v[138:139], v[202:203]
	v_pk_fma_f32 v[26:27], v[24:25], v[136:137], v[54:55]
	v_cvt_pk_bf16_f32 v24, v28, v29
	v_lshl_add_u64 v[28:29], s[6:7], 0, v[226:227]
	v_cvt_pk_bf16_f32 v25, v30, v31
	v_cvt_pk_bf16_f32 v26, v26, v27
	v_cvt_pk_bf16_f32 v27, v200, v201
	v_lshl_add_u64 v[28:29], v[28:29], 0, v[154:155]
	global_store_dwordx4 v[28:29], v[24:27], off
	v_lshlrev_b32_e32 v30, 16, v206
	v_and_b32_e32 v31, 0xffff0000, v206
	v_lshlrev_b32_e32 v24, 16, v204
	v_and_b32_e32 v25, 0xffff0000, v204
	v_lshlrev_b32_e32 v26, 16, v205
	v_and_b32_e32 v27, 0xffff0000, v205
	v_lshlrev_b32_e32 v200, 16, v207
	v_and_b32_e32 v201, 0xffff0000, v207
	v_pk_fma_f32 v[22:23], v[22:23], v[134:135], v[26:27]
	v_pk_fma_f32 v[20:21], v[20:21], v[132:133], v[24:25]
	v_pk_fma_f32 v[24:25], v[18:19], v[130:131], v[200:201]
	v_pk_fma_f32 v[18:19], v[16:17], v[128:129], v[30:31]
	v_cvt_pk_bf16_f32 v16, v20, v21
	v_cvt_pk_bf16_f32 v17, v22, v23
	v_lshlrev_b32_e32 v20, 16, v210
	v_cvt_pk_bf16_f32 v18, v18, v19
	v_cvt_pk_bf16_f32 v19, v24, v25
	global_store_dwordx4 v[28:29], v[16:19], off offset:256
	v_and_b32_e32 v21, 0xffff0000, v210
	v_lshlrev_b32_e32 v22, 16, v211
	v_lshlrev_b32_e32 v16, 16, v208
	v_and_b32_e32 v17, 0xffff0000, v208
	v_and_b32_e32 v23, 0xffff0000, v211
	v_pk_fma_f32 v[12:13], v[12:13], v[140:141], v[16:17]
	v_lshlrev_b32_e32 v18, 16, v209
	v_and_b32_e32 v19, 0xffff0000, v209
	v_pk_fma_f32 v[16:17], v[10:11], v[138:139], v[22:23]
	v_pk_fma_f32 v[10:11], v[8:9], v[136:137], v[20:21]
	v_cvt_pk_bf16_f32 v8, v12, v13
	v_lshl_add_u64 v[12:13], s[6:7], 0, v[228:229]
	v_pk_fma_f32 v[14:15], v[14:15], v[142:143], v[18:19]
	v_lshl_add_u64 v[12:13], v[12:13], 0, v[154:155]
	v_cvt_pk_bf16_f32 v9, v14, v15
	v_cvt_pk_bf16_f32 v10, v10, v11
	v_cvt_pk_bf16_f32 v11, v16, v17
	global_store_dwordx4 v[12:13], v[8:11], off
	v_lshlrev_b32_e32 v14, 16, v224
	v_and_b32_e32 v15, 0xffff0000, v224
	v_lshlrev_b32_e32 v8, 16, v222
	v_and_b32_e32 v9, 0xffff0000, v222
	v_lshlrev_b32_e32 v16, 16, v225
	v_and_b32_e32 v17, 0xffff0000, v225
	v_lshlrev_b32_e32 v10, 16, v223
	v_and_b32_e32 v11, 0xffff0000, v223
	v_pk_fma_f32 v[4:5], v[4:5], v[132:133], v[8:9]
	v_pk_fma_f32 v[8:9], v[2:3], v[130:131], v[16:17]
	v_pk_fma_f32 v[2:3], v[0:1], v[128:129], v[14:15]
	v_pk_fma_f32 v[6:7], v[6:7], v[134:135], v[10:11]
	v_cvt_pk_bf16_f32 v0, v4, v5
	s_nop 0
	v_cvt_pk_bf16_f32 v1, v6, v7
	v_cvt_pk_bf16_f32 v2, v2, v3
	v_cvt_pk_bf16_f32 v3, v8, v9
	global_store_dwordx4 v[12:13], v[0:3], off offset:256
	v_readlane_b32 s90, v255, 36
	s_and_b64 vcc, exec, s[38:39]
	s_mov_b64 s[18:19], -1
	v_readlane_b32 s91, v255, 37
	s_mov_b64 s[38:39], 0x800
	s_cbranch_vccnz .LBB0_33
	s_andn2_b64 vcc, exec, s[8:9]
	s_cbranch_vccnz .LBB0_32
	s_barrier
	s_branch .LBB0_32

; __device__ __forceinline__ float fast_sigmoid(float x) { return __builtin_amdgcn_rcpf(1.0f + __builtin_amdgcn_exp2f(-x * LOG2E)); }
; __device__ __forceinline__ u32x4 pack8(const f32x4 a, const f32x4 b) { u32x4 w; w.x = cvt_pk_bf16(a[0], a[1]); w.y = cvt_pk_bf16(a[2], a[3]); w.z = cvt_pk_bf16(b[0], b[1]); w.w = cvt_pk_bf16(b[2], b[3]); return w; }
;     __device__ __forceinline__ bool operator()(f32x4 (&acc)[2][2][4][2], const Unit& u, int wr, int wc, int fr, int fq) const {
;         const int row0 = u.pm * 256 + wr * 64 + fr, c0 = u.pn * 128 + wc * 32 + fq * 8;
; #pragma unroll
;         for (int ai = 0; ai < 2; ++ai)
; #pragma unroll
;             for (int m = 0; m < 4; ++m) {
;                 f32x4 h0, h1;
; #pragma unroll
;                 for (int j = 0; j < 4; ++j) {
;                     const float g0 = acc[ai][0][m][0][j], g1 = acc[ai][0][m][1][j];
;                     h0[j] = g0 * fast_sigmoid(g0) * acc[ai][1][m][0][j]; h1[j] = g1 * fast_sigmoid(g1) * acc[ai][1][m][1][j];
;                 }
;                 *(u32x4*)(HID + (size_t)(row0 + ai * 128 + m * 16) * DFF + c0) = pack8(h0, h1);
;             }
.LBB0_94:
	v_mul_f32_e32 v149, 0xbfb8aa3b, v124
	v_exp_f32_e32 v149, v149
	v_readlane_b32 s14, v254, 4
	v_lshl_or_b32 v150, s18, 7, v147
	v_readlane_b32 s15, v254, 5
	v_add_f32_e32 v149, 1.0, v149
	v_rcp_f32_e32 v149, v149
	v_lshl_add_u32 v148, s28, 8, v138
	v_ashrrev_i32_e32 v151, 31, v150
	s_mov_b64 s[18:19], -1
	v_mul_f32_e32 v124, v124, v149
	v_mul_f32_e32 v120, v124, v120
	v_mul_f32_e32 v124, 0xbfb8aa3b, v116
	v_exp_f32_e32 v124, v124
	s_andn2_b64 vcc, exec, s[38:39]
	v_readlane_b32 s97, v255, 18
	v_add_f32_e32 v124, 1.0, v124
	v_rcp_f32_e32 v124, v124
	s_nop 0
	v_mul_f32_e32 v116, v116, v124
	v_mul_f32_e32 v112, v116, v112
	v_mul_f32_e32 v116, 0xbfb8aa3b, v125
	v_exp_f32_e32 v116, v116
	s_nop 0
	v_add_f32_e32 v116, 1.0, v116
	v_rcp_f32_e32 v116, v116
	s_nop 0
	v_mul_f32_e32 v116, v125, v116
	v_mul_f32_e32 v116, v116, v121
	v_mul_f32_e32 v121, 0xbfb8aa3b, v117
	v_exp_f32_e32 v121, v121
	v_cvt_pk_bf16_f32 v116, v120, v116
	s_nop 0
	v_add_f32_e32 v121, 1.0, v121
	v_rcp_f32_e32 v121, v121
	s_nop 0
	v_mul_f32_e32 v117, v117, v121
	v_mul_f32_e32 v121, 0xbfb8aa3b, v118
	v_exp_f32_e32 v121, v121
	v_mul_f32_e32 v113, v117, v113
	v_mul_f32_e32 v117, 0xbfb8aa3b, v126
	v_exp_f32_e32 v117, v117
	v_add_f32_e32 v121, 1.0, v121
	v_rcp_f32_e32 v121, v121
	v_add_f32_e32 v117, 1.0, v117
	v_rcp_f32_e32 v117, v117
	v_mul_f32_e32 v118, v118, v121
	v_mul_f32_e32 v114, v118, v114
	v_mul_f32_e32 v118, 0xbfb8aa3b, v127
	v_exp_f32_e32 v118, v118
	v_mul_f32_e32 v121, 0xbfb8aa3b, v119
	v_exp_f32_e32 v121, v121
	v_mul_f32_e32 v117, v126, v117
	v_add_f32_e32 v118, 1.0, v118
	v_rcp_f32_e32 v118, v118
	v_add_f32_e32 v121, 1.0, v121
	v_rcp_f32_e32 v121, v121
	v_mul_f32_e32 v117, v117, v122
	v_mul_f32_e32 v118, v127, v118
	v_mul_f32_e32 v118, v118, v123
	v_mul_f32_e32 v119, v119, v121
	v_mul_f32_e32 v115, v119, v115
	v_cvt_pk_bf16_f32 v117, v117, v118
	v_cvt_pk_bf16_f32 v118, v112, v113
	v_mov_b64_e32 v[112:113], s[14:15]
	v_cvt_pk_bf16_f32 v119, v114, v115
	v_mad_i64_i32 v[120:121], s[14:15], v148, s17, v[112:113]
	v_lshlrev_b64 v[114:115], 1, v[150:151]
	v_lshl_add_u64 v[120:121], v[120:121], 0, v[114:115]
	global_store_dwordx4 v[120:121], v[116:119], off
	s_nop 1
	v_mul_f32_e32 v116, 0xbfb8aa3b, v108
	v_exp_f32_e32 v116, v116
	s_nop 0
	v_add_f32_e32 v116, 1.0, v116
	v_rcp_f32_e32 v116, v116
	s_nop 0
	v_mul_f32_e32 v108, v108, v116
	v_mul_f32_e32 v104, v108, v104
	v_mul_f32_e32 v108, 0xbfb8aa3b, v100
	v_exp_f32_e32 v108, v108
	s_nop 0
	v_add_f32_e32 v108, 1.0, v108
	v_rcp_f32_e32 v108, v108
	s_nop 0
	v_mul_f32_e32 v100, v100, v108
	v_mul_f32_e32 v100, v100, v96
	v_mul_f32_e32 v96, 0xbfb8aa3b, v109
	v_exp_f32_e32 v96, v96
	s_nop 0
	v_add_f32_e32 v96, 1.0, v96
	v_rcp_f32_e32 v96, v96
	s_nop 0
	v_mul_f32_e32 v96, v109, v96
	v_mul_f32_e32 v96, v96, v105
	v_mul_f32_e32 v105, 0xbfb8aa3b, v101
	v_exp_f32_e32 v105, v105
	v_cvt_pk_bf16_f32 v96, v104, v96
	s_nop 0
	v_add_f32_e32 v105, 1.0, v105
	v_rcp_f32_e32 v105, v105
	s_nop 0
	v_mul_f32_e32 v101, v101, v105
	v_mul_f32_e32 v105, 0xbfb8aa3b, v102
	v_exp_f32_e32 v105, v105
	v_mul_f32_e32 v101, v101, v97
	v_mul_f32_e32 v97, 0xbfb8aa3b, v110
	v_exp_f32_e32 v97, v97
	v_add_f32_e32 v105, 1.0, v105
	v_rcp_f32_e32 v105, v105
	v_add_f32_e32 v97, 1.0, v97
	v_rcp_f32_e32 v97, v97
	v_mul_f32_e32 v102, v102, v105
	v_mul_f32_e32 v102, v102, v98
	v_mul_f32_e32 v98, 0xbfb8aa3b, v111
	v_exp_f32_e32 v98, v98
	v_mul_f32_e32 v105, 0xbfb8aa3b, v103
	v_exp_f32_e32 v105, v105
	v_mul_f32_e32 v97, v110, v97
	v_add_f32_e32 v98, 1.0, v98
	v_rcp_f32_e32 v98, v98
	v_add_f32_e32 v105, 1.0, v105
	v_rcp_f32_e32 v105, v105
	v_mul_f32_e32 v97, v97, v106
	v_mul_f32_e32 v98, v111, v98
	v_mul_f32_e32 v98, v98, v107
	v_cvt_pk_bf16_f32 v97, v97, v98
	v_cvt_pk_bf16_f32 v98, v100, v101
	v_or_b32_e32 v100, 16, v148
	v_mul_f32_e32 v103, v103, v105
	v_mad_i64_i32 v[100:101], s[14:15], v100, s17, v[112:113]
	v_mul_f32_e32 v99, v103, v99
	v_lshl_add_u64 v[100:101], v[100:101], 0, v[114:115]
	v_cvt_pk_bf16_f32 v99, v102, v99
	global_store_dwordx4 v[100:101], v[96:99], off
	s_nop 1
	v_mul_f32_e32 v96, 0xbfb8aa3b, v92
	v_exp_f32_e32 v96, v96
	s_nop 0
	v_add_f32_e32 v96, 1.0, v96
	v_rcp_f32_e32 v96, v96
	s_nop 0
	v_mul_f32_e32 v92, v92, v96
	v_mul_f32_e32 v88, v92, v88
	v_mul_f32_e32 v92, 0xbfb8aa3b, v84
	v_exp_f32_e32 v92, v92
	s_nop 0
	v_add_f32_e32 v92, 1.0, v92
	v_rcp_f32_e32 v92, v92
	s_nop 0
	v_mul_f32_e32 v84, v84, v92
	v_mul_f32_e32 v84, v84, v80
	v_mul_f32_e32 v80, 0xbfb8aa3b, v93
	v_exp_f32_e32 v80, v80
	s_nop 0
	v_add_f32_e32 v80, 1.0, v80
	v_rcp_f32_e32 v80, v80
	s_nop 0
	v_mul_f32_e32 v80, v93, v80
	v_mul_f32_e32 v80, v80, v89
	v_mul_f32_e32 v89, 0xbfb8aa3b, v85
	v_exp_f32_e32 v89, v89
	v_cvt_pk_bf16_f32 v80, v88, v80
	s_nop 0
	v_add_f32_e32 v89, 1.0, v89
	v_rcp_f32_e32 v89, v89
	s_nop 0
	v_mul_f32_e32 v85, v85, v89
	v_mul_f32_e32 v89, 0xbfb8aa3b, v86
	v_exp_f32_e32 v89, v89
	v_mul_f32_e32 v85, v85, v81
	v_mul_f32_e32 v81, 0xbfb8aa3b, v94
	v_exp_f32_e32 v81, v81
	v_add_f32_e32 v89, 1.0, v89
	v_rcp_f32_e32 v89, v89
	v_add_f32_e32 v81, 1.0, v81
	v_rcp_f32_e32 v81, v81
	v_mul_f32_e32 v86, v86, v89
	v_mul_f32_e32 v86, v86, v82
	v_mul_f32_e32 v82, 0xbfb8aa3b, v95
	v_exp_f32_e32 v82, v82
	v_mul_f32_e32 v89, 0xbfb8aa3b, v87
	v_exp_f32_e32 v89, v89
	v_mul_f32_e32 v81, v94, v81
	v_add_f32_e32 v82, 1.0, v82
	v_rcp_f32_e32 v82, v82
	v_add_f32_e32 v89, 1.0, v89
	v_rcp_f32_e32 v89, v89
	v_mul_f32_e32 v81, v81, v90
	v_mul_f32_e32 v82, v95, v82
	v_mul_f32_e32 v82, v82, v91
	v_cvt_pk_bf16_f32 v81, v81, v82
	v_cvt_pk_bf16_f32 v82, v84, v85
	v_or_b32_e32 v84, 32, v148
	v_mul_f32_e32 v87, v87, v89
	v_mad_i64_i32 v[84:85], s[14:15], v84, s17, v[112:113]
	v_mul_f32_e32 v83, v87, v83
; __device__ __forceinline__ float fast_sigmoid(float x) { return __builtin_amdgcn_rcpf(1.0f + __builtin_amdgcn_exp2f(-x * LOG2E)); }
; __device__ __forceinline__ u32x4 pack8(const f32x4 a, const f32x4 b) { u32x4 w; w.x = cvt_pk_bf16(a[0], a[1]); w.y = cvt_pk_bf16(a[2], a[3]); w.z = cvt_pk_bf16(b[0], b[1]); w.w = cvt_pk_bf16(b[2], b[3]); return w; }
;     __device__ __forceinline__ bool operator()(f32x4 (&acc)[2][2][4][2], const Unit& u, int wr, int wc, int fr, int fq) const {
;     ...
;             for (int m = 0; m < 4; ++m) {
;                 f32x4 h0, h1;
; #pragma unroll
;                 for (int j = 0; j < 4; ++j) {
;                     const float g0 = acc[ai][0][m][0][j], g1 = acc[ai][0][m][1][j];
;                     h0[j] = g0 * fast_sigmoid(g0) * acc[ai][1][m][0][j]; h1[j] = g1 * fast_sigmoid(g1) * acc[ai][1][m][1][j];
;                 }
;                 *(u32x4*)(HID + (size_t)(row0 + ai * 128 + m * 16) * DFF + c0) = pack8(h0, h1);
;             }
	v_lshl_add_u64 v[84:85], v[84:85], 0, v[114:115]
	v_cvt_pk_bf16_f32 v83, v86, v83
	global_store_dwordx4 v[84:85], v[80:83], off
	s_nop 1
	v_mul_f32_e32 v80, 0xbfb8aa3b, v76
	v_exp_f32_e32 v80, v80
	s_nop 0
	v_add_f32_e32 v80, 1.0, v80
	v_rcp_f32_e32 v80, v80
	s_nop 0
	v_mul_f32_e32 v76, v76, v80
	v_mul_f32_e32 v72, v76, v72
	v_mul_f32_e32 v76, 0xbfb8aa3b, v68
	v_exp_f32_e32 v76, v76
	s_nop 0
	v_add_f32_e32 v76, 1.0, v76
	v_rcp_f32_e32 v76, v76
	s_nop 0
	v_mul_f32_e32 v68, v68, v76
	v_mul_f32_e32 v68, v68, v64
	v_mul_f32_e32 v64, 0xbfb8aa3b, v77
	v_exp_f32_e32 v64, v64
	s_nop 0
	v_add_f32_e32 v64, 1.0, v64
	v_rcp_f32_e32 v64, v64
	s_nop 0
	v_mul_f32_e32 v64, v77, v64
	v_mul_f32_e32 v64, v64, v73
	v_mul_f32_e32 v73, 0xbfb8aa3b, v69
	v_exp_f32_e32 v73, v73
	v_cvt_pk_bf16_f32 v64, v72, v64
	s_nop 0
	v_add_f32_e32 v73, 1.0, v73
	v_rcp_f32_e32 v73, v73
	s_nop 0
	v_mul_f32_e32 v69, v69, v73
	v_mul_f32_e32 v73, 0xbfb8aa3b, v70
	v_exp_f32_e32 v73, v73
	v_mul_f32_e32 v69, v69, v65
	v_mul_f32_e32 v65, 0xbfb8aa3b, v78
	v_exp_f32_e32 v65, v65
	v_add_f32_e32 v73, 1.0, v73
	v_rcp_f32_e32 v73, v73
	v_add_f32_e32 v65, 1.0, v65
	v_rcp_f32_e32 v65, v65
	v_mul_f32_e32 v70, v70, v73
	v_mul_f32_e32 v70, v70, v66
	v_mul_f32_e32 v66, 0xbfb8aa3b, v79
	v_exp_f32_e32 v66, v66
	v_mul_f32_e32 v73, 0xbfb8aa3b, v71
	v_exp_f32_e32 v73, v73
	v_mul_f32_e32 v65, v78, v65
	v_add_f32_e32 v66, 1.0, v66
	v_rcp_f32_e32 v66, v66
	v_add_f32_e32 v73, 1.0, v73
	v_rcp_f32_e32 v73, v73
	v_mul_f32_e32 v65, v65, v74
	v_mul_f32_e32 v66, v79, v66
	v_mul_f32_e32 v66, v66, v75
	v_cvt_pk_bf16_f32 v65, v65, v66
	v_cvt_pk_bf16_f32 v66, v68, v69
	v_or_b32_e32 v68, 48, v148
	v_mul_f32_e32 v71, v71, v73
	v_mad_i64_i32 v[68:69], s[14:15], v68, s17, v[112:113]
	v_mul_f32_e32 v67, v71, v67
	v_lshl_add_u64 v[68:69], v[68:69], 0, v[114:115]
	v_cvt_pk_bf16_f32 v67, v70, v67
	global_store_dwordx4 v[68:69], v[64:67], off
	s_nop 1
	v_mul_f32_e32 v65, 0xbfb8aa3b, v60
	v_exp_f32_e32 v65, v65
	v_add_u32_e32 v64, 0x80, v148
	v_add_f32_e32 v65, 1.0, v65
	v_rcp_f32_e32 v65, v65
	s_nop 0
	v_mul_f32_e32 v60, v60, v65
	v_mul_f32_e32 v56, v60, v56
	v_mul_f32_e32 v60, 0xbfb8aa3b, v52
	v_exp_f32_e32 v60, v60
	s_nop 0
	v_add_f32_e32 v60, 1.0, v60
	v_rcp_f32_e32 v60, v60
	s_nop 0
	v_mul_f32_e32 v52, v52, v60
	v_mul_f32_e32 v52, v52, v48
	v_mul_f32_e32 v48, 0xbfb8aa3b, v61
	v_exp_f32_e32 v48, v48
	s_nop 0
	v_add_f32_e32 v48, 1.0, v48
	v_rcp_f32_e32 v48, v48
	s_nop 0
	v_mul_f32_e32 v48, v61, v48
	v_mul_f32_e32 v48, v48, v57
	v_mul_f32_e32 v57, 0xbfb8aa3b, v53
	v_exp_f32_e32 v57, v57
	v_cvt_pk_bf16_f32 v48, v56, v48
	s_nop 0
	v_add_f32_e32 v57, 1.0, v57
	v_rcp_f32_e32 v57, v57
	s_nop 0
	v_mul_f32_e32 v53, v53, v57
	v_mul_f32_e32 v57, 0xbfb8aa3b, v54
	v_exp_f32_e32 v57, v57
	v_mul_f32_e32 v53, v53, v49
	v_mul_f32_e32 v49, 0xbfb8aa3b, v62
	v_exp_f32_e32 v49, v49
	v_add_f32_e32 v57, 1.0, v57
	v_rcp_f32_e32 v57, v57
	v_add_f32_e32 v49, 1.0, v49
	v_rcp_f32_e32 v49, v49
	v_mul_f32_e32 v54, v54, v57
	v_mul_f32_e32 v54, v54, v50
	v_mul_f32_e32 v50, 0xbfb8aa3b, v63
	v_exp_f32_e32 v50, v50
	v_mul_f32_e32 v57, 0xbfb8aa3b, v55
	v_exp_f32_e32 v57, v57
	v_mul_f32_e32 v49, v62, v49
	v_add_f32_e32 v50, 1.0, v50
	v_rcp_f32_e32 v50, v50
	v_add_f32_e32 v57, 1.0, v57
	v_rcp_f32_e32 v57, v57
	v_mul_f32_e32 v49, v49, v58
	v_mul_f32_e32 v50, v63, v50
	v_mul_f32_e32 v50, v50, v59
	v_mul_f32_e32 v55, v55, v57
	v_cvt_pk_bf16_f32 v49, v49, v50
	v_cvt_pk_bf16_f32 v50, v52, v53
	v_mad_i64_i32 v[52:53], s[14:15], v64, s17, v[112:113]
	v_mul_f32_e32 v51, v55, v51
	v_lshl_add_u64 v[52:53], v[52:53], 0, v[114:115]
	v_cvt_pk_bf16_f32 v51, v54, v51
	global_store_dwordx4 v[52:53], v[48:51], off
	s_nop 1
	v_mul_f32_e32 v48, 0xbfb8aa3b, v44
	v_exp_f32_e32 v48, v48
	s_nop 0
	v_add_f32_e32 v48, 1.0, v48
	v_rcp_f32_e32 v48, v48
	s_nop 0
	v_mul_f32_e32 v44, v44, v48
	v_mul_f32_e32 v40, v44, v40
	v_mul_f32_e32 v44, 0xbfb8aa3b, v36
	v_exp_f32_e32 v44, v44
	s_nop 0
	v_add_f32_e32 v44, 1.0, v44
	v_rcp_f32_e32 v44, v44
	s_nop 0
	v_mul_f32_e32 v36, v36, v44
	v_mul_f32_e32 v36, v36, v32
	v_mul_f32_e32 v32, 0xbfb8aa3b, v45
	v_exp_f32_e32 v32, v32
	s_nop 0
	v_add_f32_e32 v32, 1.0, v32
	v_rcp_f32_e32 v32, v32
	s_nop 0
	v_mul_f32_e32 v32, v45, v32
	v_mul_f32_e32 v32, v32, v41
	v_mul_f32_e32 v41, 0xbfb8aa3b, v37
	v_exp_f32_e32 v41, v41
	v_cvt_pk_bf16_f32 v32, v40, v32
	s_nop 0
	v_add_f32_e32 v41, 1.0, v41
	v_rcp_f32_e32 v41, v41
	s_nop 0
	v_mul_f32_e32 v37, v37, v41
	v_mul_f32_e32 v41, 0xbfb8aa3b, v38
	v_exp_f32_e32 v41, v41
; __device__ __forceinline__ float fast_sigmoid(float x) { return __builtin_amdgcn_rcpf(1.0f + __builtin_amdgcn_exp2f(-x * LOG2E)); }
; __device__ __forceinline__ u32x4 pack8(const f32x4 a, const f32x4 b) { u32x4 w; w.x = cvt_pk_bf16(a[0], a[1]); w.y = cvt_pk_bf16(a[2], a[3]); w.z = cvt_pk_bf16(b[0], b[1]); w.w = cvt_pk_bf16(b[2], b[3]); return w; }
; template <int NT, class Epi>
; __device__ __forceinline__ void gemm_phase(LAS unsigned char* lds, const int K, const Sched& S, const Epi& E, const int wave_s) {
;     ...
;         const bool keep = E(acc, cur, wr, wc, fr, fq);
;         __builtin_amdgcn_s_waitcnt(0x0F70);
;         if (!has_next) break;
;     __device__ __forceinline__ bool operator()(f32x4 (&acc)[2][2][4][2], const Unit& u, int wr, int wc, int fr, int fq) const {
;     ...
;             for (int m = 0; m < 4; ++m) {
;                 f32x4 h0, h1;
; #pragma unroll
;                 for (int j = 0; j < 4; ++j) {
;                     const float g0 = acc[ai][0][m][0][j], g1 = acc[ai][0][m][1][j];
;                     h0[j] = g0 * fast_sigmoid(g0) * acc[ai][1][m][0][j]; h1[j] = g1 * fast_sigmoid(g1) * acc[ai][1][m][1][j];
;                 }
;                 *(u32x4*)(HID + (size_t)(row0 + ai * 128 + m * 16) * DFF + c0) = pack8(h0, h1);
;             }
;         return false;
	v_mul_f32_e32 v37, v37, v33
	v_mul_f32_e32 v33, 0xbfb8aa3b, v46
	v_exp_f32_e32 v33, v33
	v_add_f32_e32 v41, 1.0, v41
	v_rcp_f32_e32 v41, v41
	v_add_f32_e32 v33, 1.0, v33
	v_rcp_f32_e32 v33, v33
	v_mul_f32_e32 v38, v38, v41
	v_mul_f32_e32 v38, v38, v34
	v_mul_f32_e32 v34, 0xbfb8aa3b, v47
	v_exp_f32_e32 v34, v34
	v_mul_f32_e32 v41, 0xbfb8aa3b, v39
	v_exp_f32_e32 v41, v41
	v_mul_f32_e32 v33, v46, v33
	v_add_f32_e32 v34, 1.0, v34
	v_rcp_f32_e32 v34, v34
	v_add_f32_e32 v41, 1.0, v41
	v_rcp_f32_e32 v41, v41
	v_mul_f32_e32 v33, v33, v42
	v_mul_f32_e32 v34, v47, v34
	v_mul_f32_e32 v34, v34, v43
	v_cvt_pk_bf16_f32 v33, v33, v34
	v_cvt_pk_bf16_f32 v34, v36, v37
	v_add_u32_e32 v36, 0x90, v148
	v_mul_f32_e32 v39, v39, v41
	v_mad_i64_i32 v[36:37], s[14:15], v36, s17, v[112:113]
	v_mul_f32_e32 v35, v39, v35
	v_lshl_add_u64 v[36:37], v[36:37], 0, v[114:115]
	v_cvt_pk_bf16_f32 v35, v38, v35
	global_store_dwordx4 v[36:37], v[32:35], off
	s_nop 1
	v_mul_f32_e32 v32, 0xbfb8aa3b, v28
	v_exp_f32_e32 v32, v32
	s_nop 0
	v_add_f32_e32 v32, 1.0, v32
	v_rcp_f32_e32 v32, v32
	s_nop 0
	v_mul_f32_e32 v28, v28, v32
	v_mul_f32_e32 v24, v28, v24
	v_mul_f32_e32 v28, 0xbfb8aa3b, v20
	v_exp_f32_e32 v28, v28
	s_nop 0
	v_add_f32_e32 v28, 1.0, v28
	v_rcp_f32_e32 v28, v28
	s_nop 0
	v_mul_f32_e32 v20, v20, v28
	v_mul_f32_e32 v20, v20, v16
	v_mul_f32_e32 v16, 0xbfb8aa3b, v29
	v_exp_f32_e32 v16, v16
	s_nop 0
	v_add_f32_e32 v16, 1.0, v16
	v_rcp_f32_e32 v16, v16
	s_nop 0
	v_mul_f32_e32 v16, v29, v16
	v_mul_f32_e32 v16, v16, v25
	v_mul_f32_e32 v25, 0xbfb8aa3b, v21
	v_exp_f32_e32 v25, v25
	v_cvt_pk_bf16_f32 v16, v24, v16
	s_nop 0
	v_add_f32_e32 v25, 1.0, v25
	v_rcp_f32_e32 v25, v25
	s_nop 0
	v_mul_f32_e32 v21, v21, v25
	v_mul_f32_e32 v25, 0xbfb8aa3b, v22
	v_exp_f32_e32 v25, v25
	v_mul_f32_e32 v21, v21, v17
	v_mul_f32_e32 v17, 0xbfb8aa3b, v30
	v_exp_f32_e32 v17, v17
	v_add_f32_e32 v25, 1.0, v25
	v_rcp_f32_e32 v25, v25
	v_add_f32_e32 v17, 1.0, v17
	v_rcp_f32_e32 v17, v17
	v_mul_f32_e32 v22, v22, v25
	v_mul_f32_e32 v22, v22, v18
	v_mul_f32_e32 v18, 0xbfb8aa3b, v31
	v_exp_f32_e32 v18, v18
	v_mul_f32_e32 v25, 0xbfb8aa3b, v23
	v_exp_f32_e32 v25, v25
	v_mul_f32_e32 v17, v30, v17
	v_add_f32_e32 v18, 1.0, v18
	v_rcp_f32_e32 v18, v18
	v_add_f32_e32 v25, 1.0, v25
	v_rcp_f32_e32 v25, v25
	v_mul_f32_e32 v17, v17, v26
	v_mul_f32_e32 v18, v31, v18
	v_mul_f32_e32 v18, v18, v27
	v_cvt_pk_bf16_f32 v17, v17, v18
	v_cvt_pk_bf16_f32 v18, v20, v21
	v_add_u32_e32 v20, 0xa0, v148
	v_mul_f32_e32 v23, v23, v25
	v_mad_i64_i32 v[20:21], s[14:15], v20, s17, v[112:113]
	v_mul_f32_e32 v19, v23, v19
	v_lshl_add_u64 v[20:21], v[20:21], 0, v[114:115]
	v_cvt_pk_bf16_f32 v19, v22, v19
	global_store_dwordx4 v[20:21], v[16:19], off
	s_nop 1
	v_mul_f32_e32 v16, 0xbfb8aa3b, v12
	v_exp_f32_e32 v16, v16
	s_nop 0
	v_add_f32_e32 v16, 1.0, v16
	v_rcp_f32_e32 v16, v16
	s_nop 0
	v_mul_f32_e32 v12, v12, v16
	v_mul_f32_e32 v8, v12, v8
	v_mul_f32_e32 v12, 0xbfb8aa3b, v4
	v_exp_f32_e32 v12, v12
	s_nop 0
	v_add_f32_e32 v12, 1.0, v12
	v_rcp_f32_e32 v12, v12
	s_nop 0
	v_mul_f32_e32 v4, v4, v12
	v_mul_f32_e32 v4, v4, v0
	v_mul_f32_e32 v0, 0xbfb8aa3b, v13
	v_exp_f32_e32 v0, v0
	s_nop 0
	v_add_f32_e32 v0, 1.0, v0
	v_rcp_f32_e32 v0, v0
	s_nop 0
	v_mul_f32_e32 v0, v13, v0
	v_mul_f32_e32 v0, v0, v9
	v_mul_f32_e32 v9, 0xbfb8aa3b, v5
	v_exp_f32_e32 v9, v9
	v_cvt_pk_bf16_f32 v0, v8, v0
	s_nop 0
	v_add_f32_e32 v9, 1.0, v9
	v_rcp_f32_e32 v9, v9
	s_nop 0
	v_mul_f32_e32 v5, v5, v9
	v_mul_f32_e32 v9, 0xbfb8aa3b, v6
	v_exp_f32_e32 v9, v9
	v_mul_f32_e32 v5, v5, v1
	v_mul_f32_e32 v1, 0xbfb8aa3b, v14
	v_exp_f32_e32 v1, v1
	v_add_f32_e32 v9, 1.0, v9
	v_rcp_f32_e32 v9, v9
	v_add_f32_e32 v1, 1.0, v1
	v_rcp_f32_e32 v1, v1
	v_mul_f32_e32 v6, v6, v9
	v_mul_f32_e32 v6, v6, v2
	v_mul_f32_e32 v2, 0xbfb8aa3b, v15
	v_exp_f32_e32 v2, v2
	v_mul_f32_e32 v9, 0xbfb8aa3b, v7
	v_exp_f32_e32 v9, v9
	v_mul_f32_e32 v1, v14, v1
	v_add_f32_e32 v2, 1.0, v2
	v_rcp_f32_e32 v2, v2
	v_add_f32_e32 v9, 1.0, v9
	v_rcp_f32_e32 v9, v9
	v_mul_f32_e32 v1, v1, v10
	v_mul_f32_e32 v2, v15, v2
	v_mul_f32_e32 v2, v2, v11
	v_cvt_pk_bf16_f32 v1, v1, v2
	v_cvt_pk_bf16_f32 v2, v4, v5
	v_add_u32_e32 v4, 0xb0, v148
	v_mul_f32_e32 v7, v7, v9
	v_mad_i64_i32 v[4:5], s[14:15], v4, s17, v[112:113]
	v_mul_f32_e32 v3, v7, v3
	v_lshl_add_u64 v[4:5], v[4:5], 0, v[114:115]
	v_cvt_pk_bf16_f32 v3, v6, v3
	global_store_dwordx4 v[4:5], v[0:3], off
	s_cbranch_vccnz .LBB0_87
	s_andn2_b64 vcc, exec, s[0:1]
	s_cbranch_vccnz .LBB0_86
	s_barrier
	s_branch .LBB0_86

; __device__ __forceinline__ float bf_lo(unsigned u) { return __uint_as_float(u << 16); }
; __device__ __forceinline__ float bf_hi(unsigned u) { return __uint_as_float(u & 0xffff0000u); }
; __device__ __forceinline__ u32x4 pack8(const f32x4 a, const f32x4 b) { u32x4 w; w.x = cvt_pk_bf16(a[0], a[1]); w.y = cvt_pk_bf16(a[2], a[3]); w.z = cvt_pk_bf16(b[0], b[1]); w.w = cvt_pk_bf16(b[2], b[3]); return w; }
;     __device__ __forceinline__ bool operator()(f32x4 (&acc)[2][2][4][2], const Unit& u, int wr, int wc, int fr, int fq) const {
;     ...
;         const int vec = u.pm >> 5;
;         const int row0 = u.pm * 256 + wr * 64 + fr, c0 = u.pn * 256 + wc * 32 + fq * 8;
;         const float* gp = gate + vec * 12288 + c0;
;         f32x4 gv[2][2];
; #pragma unroll
;         for (int bj = 0; bj < 2; ++bj) { gv[bj][0] = *(const f32x4*)(gp + bj * 128); gv[bj][1] = *(const f32x4*)(gp + bj * 128 + 4); }
; #pragma unroll
;         for (int b4 = 0; b4 < 4; ++b4) {
;             const int ai = b4 >> 1, mh = (b4 & 1) * 2;
;             u32x4 xq[2][2];
; #pragma unroll
;             for (int mm = 0; mm < 2; ++mm)
; #pragma unroll
;                 for (int bj = 0; bj < 2; ++bj) xq[mm][bj] = *(const u32x4*)(xb + (size_t)(row0 + ai * 128 + (mh + mm) * 16) * D + c0 + bj * 128);
;             __builtin_amdgcn_sched_barrier(0);
; #pragma unroll
;             for (int mm = 0; mm < 2; ++mm)
; #pragma unroll
;                 for (int bj = 0; bj < 2; ++bj)
;                 { const u32x4 q = xq[mm][bj]; const f32x4 x0 = (f32x4){bf_lo(q.x), bf_hi(q.x), bf_lo(q.y), bf_hi(q.y)}, x1 = (f32x4){bf_lo(q.z), bf_hi(q.z), bf_lo(q.w), bf_hi(q.w)};
;                     *(u32x4*)(xb + (size_t)(row0 + ai * 128 + (mh + mm) * 16) * D + c0 + bj * 128) = pack8(x0 + gv[bj][0] * acc[ai][bj][mh + mm][0], x1 + gv[bj][1] * acc[ai][bj][mh + mm][1]); }
;             __builtin_amdgcn_sched_barrier(0);
;         }
.LBB0_120:
	s_lshr_b32 s13, s85, 5
	s_mul_i32 s14, s13, 0x3000
	s_ashr_i32 s15, s14, 31
	s_lshl_b64 s[14:15], s[14:15], 2
	v_lshl_or_b32 v154, s86, 8, v169
	s_add_u32 s14, s2, s14
	s_addc_u32 s15, s0, s15
	v_ashrrev_i32_e32 v155, 31, v154
	v_lshl_add_u32 v174, s85, 8, v160
	v_lshl_add_u64 v[132:133], v[154:155], 2, s[14:15]
	v_lshlrev_b64 v[154:155], 1, v[154:155]
	v_ashrrev_i32_e32 v175, 31, v174
	v_lshl_add_u64 v[156:157], s[6:7], 0, v[154:155]
	v_lshlrev_b64 v[158:159], 12, v[174:175]
	v_lshl_add_u64 v[178:179], v[156:157], 0, v[158:159]
	global_load_dwordx4 v[136:139], v[132:133], off offset:16
	global_load_dwordx4 v[140:143], v[132:133], off
	global_load_dwordx4 v[128:131], v[132:133], off offset:528
	s_nop 0
	global_load_dwordx4 v[132:135], v[132:133], off offset:512
	s_nop 0
	global_load_dwordx4 v[170:173], v[178:179], off
	global_load_dwordx4 v[182:185], v[178:179], off offset:256
	v_or_b32_e32 v178, 16, v174
	v_ashrrev_i32_e32 v179, 31, v178
	v_lshlrev_b64 v[178:179], 12, v[178:179]
	v_lshl_add_u64 v[180:181], v[156:157], 0, v[178:179]
	global_load_dwordx4 v[190:193], v[180:181], off
	global_load_dwordx4 v[194:197], v[180:181], off offset:256
	v_or_b32_e32 v200, 32, v174
	v_or_b32_e32 v208, 48, v174
	v_ashrrev_i32_e32 v201, 31, v200
	v_ashrrev_i32_e32 v209, 31, v208
	v_lshlrev_b64 v[226:227], 12, v[200:201]
	v_lshlrev_b64 v[228:229], 12, v[208:209]
	v_lshl_add_u64 v[204:205], v[156:157], 0, v[226:227]
	v_lshl_add_u64 v[222:223], v[156:157], 0, v[228:229]
	global_load_dwordx4 v[200:203], v[204:205], off
	s_nop 0
	global_load_dwordx4 v[204:207], v[204:205], off offset:256
	s_nop 0
	global_load_dwordx4 v[208:211], v[222:223], off
	s_nop 0
	global_load_dwordx4 v[222:225], v[222:223], off offset:256
	s_waitcnt vmcnt(4)
	v_lshlrev_b32_e32 v180, 16, v170
	v_and_b32_e32 v181, 0xffff0000, v170
	v_lshlrev_b32_e32 v170, 16, v171
	v_and_b32_e32 v171, 0xffff0000, v171
	v_lshlrev_b32_e32 v198, 16, v172
	v_and_b32_e32 v199, 0xffff0000, v172
	v_lshlrev_b32_e32 v172, 16, v173
	v_and_b32_e32 v173, 0xffff0000, v173
	v_pk_fma_f32 v[124:125], v[124:125], v[140:141], v[180:181]
	v_pk_fma_f32 v[126:127], v[126:127], v[142:143], v[170:171]
	v_pk_fma_f32 v[170:171], v[122:123], v[138:139], v[172:173]
	v_pk_fma_f32 v[122:123], v[120:121], v[136:137], v[198:199]
	v_cvt_pk_bf16_f32 v120, v124, v125
	v_lshl_add_u64 v[124:125], s[6:7], 0, v[158:159]
	v_cvt_pk_bf16_f32 v121, v126, v127
	v_cvt_pk_bf16_f32 v122, v122, v123
	v_cvt_pk_bf16_f32 v123, v170, v171
	v_lshl_add_u64 v[124:125], v[124:125], 0, v[154:155]
	global_store_dwordx4 v[124:125], v[120:123], off
	v_lshlrev_b32_e32 v126, 16, v184
	v_and_b32_e32 v127, 0xffff0000, v184
	v_lshlrev_b32_e32 v120, 16, v182
	v_and_b32_e32 v121, 0xffff0000, v182
	v_lshlrev_b32_e32 v122, 16, v183
	v_and_b32_e32 v123, 0xffff0000, v183
	v_lshlrev_b32_e32 v170, 16, v185
	v_and_b32_e32 v171, 0xffff0000, v185
	v_pk_fma_f32 v[118:119], v[118:119], v[134:135], v[122:123]
	v_pk_fma_f32 v[116:117], v[116:117], v[132:133], v[120:121]
	v_pk_fma_f32 v[120:121], v[114:115], v[130:131], v[170:171]
	v_pk_fma_f32 v[114:115], v[112:113], v[128:129], v[126:127]
	v_cvt_pk_bf16_f32 v112, v116, v117
	v_cvt_pk_bf16_f32 v113, v118, v119
	v_lshlrev_b32_e32 v116, 16, v192
	v_cvt_pk_bf16_f32 v114, v114, v115
	v_cvt_pk_bf16_f32 v115, v120, v121
	global_store_dwordx4 v[124:125], v[112:115], off offset:256
	v_and_b32_e32 v117, 0xffff0000, v192
	v_lshlrev_b32_e32 v118, 16, v193
	v_lshlrev_b32_e32 v112, 16, v190
	v_and_b32_e32 v113, 0xffff0000, v190
	v_and_b32_e32 v119, 0xffff0000, v193
	v_pk_fma_f32 v[108:109], v[108:109], v[140:141], v[112:113]
	v_lshlrev_b32_e32 v114, 16, v191
	v_and_b32_e32 v115, 0xffff0000, v191
	v_pk_fma_f32 v[112:113], v[106:107], v[138:139], v[118:119]
	v_pk_fma_f32 v[106:107], v[104:105], v[136:137], v[116:117]
	v_cvt_pk_bf16_f32 v104, v108, v109
	v_lshl_add_u64 v[108:109], s[6:7], 0, v[178:179]
	v_pk_fma_f32 v[110:111], v[110:111], v[142:143], v[114:115]
	v_lshl_add_u64 v[108:109], v[108:109], 0, v[154:155]
	v_cvt_pk_bf16_f32 v105, v110, v111
	v_cvt_pk_bf16_f32 v106, v106, v107
	v_cvt_pk_bf16_f32 v107, v112, v113
	global_store_dwordx4 v[108:109], v[104:107], off
	v_lshlrev_b32_e32 v110, 16, v196
	v_and_b32_e32 v111, 0xffff0000, v196
	v_lshlrev_b32_e32 v104, 16, v194
	v_and_b32_e32 v105, 0xffff0000, v194
	v_lshlrev_b32_e32 v112, 16, v197
	v_and_b32_e32 v113, 0xffff0000, v197
	v_lshlrev_b32_e32 v106, 16, v195
	v_and_b32_e32 v107, 0xffff0000, v195
	v_pk_fma_f32 v[100:101], v[100:101], v[132:133], v[104:105]
	v_pk_fma_f32 v[104:105], v[98:99], v[130:131], v[112:113]
	v_pk_fma_f32 v[98:99], v[96:97], v[128:129], v[110:111]
	v_pk_fma_f32 v[102:103], v[102:103], v[134:135], v[106:107]
	v_cvt_pk_bf16_f32 v96, v100, v101
	s_nop 0
	v_cvt_pk_bf16_f32 v97, v102, v103
	v_cvt_pk_bf16_f32 v98, v98, v99
	v_cvt_pk_bf16_f32 v99, v104, v105
	global_store_dwordx4 v[108:109], v[96:99], off offset:256
	v_lshl_add_u64 v[242:243], v[158:159], 0, s[54:55]
	v_lshl_add_u64 v[250:251], v[158:159], 0, s[56:57]
	v_lshl_add_u64 v[234:235], v[156:157], 0, v[242:243]
	v_lshl_add_u64 v[246:247], v[156:157], 0, v[250:251]
	global_load_dwordx4 v[230:233], v[234:235], off
	s_nop 0
	global_load_dwordx4 v[234:237], v[234:235], off offset:256
	s_nop 0
	global_load_dwordx4 v[238:241], v[246:247], off
	s_nop 0
	global_load_dwordx4 v[246:249], v[246:247], off offset:256
	s_waitcnt vmcnt(8)
; __device__ __forceinline__ float bf_lo(unsigned u) { return __uint_as_float(u << 16); }
; __device__ __forceinline__ float bf_hi(unsigned u) { return __uint_as_float(u & 0xffff0000u); }
; __device__ __forceinline__ u32x4 pack8(const f32x4 a, const f32x4 b) { u32x4 w; w.x = cvt_pk_bf16(a[0], a[1]); w.y = cvt_pk_bf16(a[2], a[3]); w.z = cvt_pk_bf16(b[0], b[1]); w.w = cvt_pk_bf16(b[2], b[3]); return w; }
;     __device__ __forceinline__ bool operator()(f32x4 (&acc)[2][2][4][2], const Unit& u, int wr, int wc, int fr, int fq) const {
;     ...
; #pragma unroll
;             for (int mm = 0; mm < 2; ++mm)
; #pragma unroll
;                 for (int bj = 0; bj < 2; ++bj)
;                 { const u32x4 q = xq[mm][bj]; const f32x4 x0 = (f32x4){bf_lo(q.x), bf_hi(q.x), bf_lo(q.y), bf_hi(q.y)}, x1 = (f32x4){bf_lo(q.z), bf_hi(q.z), bf_lo(q.w), bf_hi(q.w)};
;                     *(u32x4*)(xb + (size_t)(row0 + ai * 128 + (mh + mm) * 16) * D + c0 + bj * 128) = pack8(x0 + gv[bj][0] * acc[ai][bj][mh + mm][0], x1 + gv[bj][1] * acc[ai][bj][mh + mm][1]); }
;             __builtin_amdgcn_sched_barrier(0);
	v_lshlrev_b32_e32 v116, 16, v200
	v_and_b32_e32 v117, 0xffff0000, v200
	v_lshlrev_b32_e32 v200, 16, v201
	v_and_b32_e32 v201, 0xffff0000, v201
	v_lshlrev_b32_e32 v118, 16, v202
	v_and_b32_e32 v119, 0xffff0000, v202
	v_lshlrev_b32_e32 v202, 16, v203
	v_and_b32_e32 v203, 0xffff0000, v203
	v_pk_fma_f32 v[92:93], v[92:93], v[140:141], v[116:117]
	v_pk_fma_f32 v[94:95], v[94:95], v[142:143], v[200:201]
	v_pk_fma_f32 v[200:201], v[90:91], v[138:139], v[202:203]
	v_pk_fma_f32 v[90:91], v[88:89], v[136:137], v[118:119]
	v_cvt_pk_bf16_f32 v88, v92, v93
	v_lshl_add_u64 v[92:93], s[6:7], 0, v[226:227]
	v_cvt_pk_bf16_f32 v89, v94, v95
	v_cvt_pk_bf16_f32 v90, v90, v91
	v_cvt_pk_bf16_f32 v91, v200, v201
	v_lshl_add_u64 v[92:93], v[92:93], 0, v[154:155]
	global_store_dwordx4 v[92:93], v[88:91], off
	v_lshlrev_b32_e32 v94, 16, v206
	v_and_b32_e32 v95, 0xffff0000, v206
	v_lshlrev_b32_e32 v88, 16, v204
	v_and_b32_e32 v89, 0xffff0000, v204
	v_lshlrev_b32_e32 v90, 16, v205
	v_and_b32_e32 v91, 0xffff0000, v205
	v_lshlrev_b32_e32 v200, 16, v207
	v_and_b32_e32 v201, 0xffff0000, v207
	v_pk_fma_f32 v[86:87], v[86:87], v[134:135], v[90:91]
	v_pk_fma_f32 v[84:85], v[84:85], v[132:133], v[88:89]
	v_pk_fma_f32 v[88:89], v[82:83], v[130:131], v[200:201]
	v_pk_fma_f32 v[82:83], v[80:81], v[128:129], v[94:95]
	v_cvt_pk_bf16_f32 v80, v84, v85
	v_cvt_pk_bf16_f32 v81, v86, v87
	v_lshlrev_b32_e32 v84, 16, v210
	v_cvt_pk_bf16_f32 v82, v82, v83
	v_cvt_pk_bf16_f32 v83, v88, v89
	global_store_dwordx4 v[92:93], v[80:83], off offset:256
	v_and_b32_e32 v85, 0xffff0000, v210
	v_lshlrev_b32_e32 v86, 16, v211
	v_lshlrev_b32_e32 v80, 16, v208
	v_and_b32_e32 v81, 0xffff0000, v208
	v_and_b32_e32 v87, 0xffff0000, v211
	v_pk_fma_f32 v[76:77], v[76:77], v[140:141], v[80:81]
	v_lshlrev_b32_e32 v82, 16, v209
	v_and_b32_e32 v83, 0xffff0000, v209
	v_pk_fma_f32 v[80:81], v[74:75], v[138:139], v[86:87]
	v_pk_fma_f32 v[74:75], v[72:73], v[136:137], v[84:85]
	v_cvt_pk_bf16_f32 v72, v76, v77
	v_lshl_add_u64 v[76:77], s[6:7], 0, v[228:229]
	v_pk_fma_f32 v[78:79], v[78:79], v[142:143], v[82:83]
	v_lshl_add_u64 v[76:77], v[76:77], 0, v[154:155]
	v_cvt_pk_bf16_f32 v73, v78, v79
	v_cvt_pk_bf16_f32 v74, v74, v75
	v_cvt_pk_bf16_f32 v75, v80, v81
	global_store_dwordx4 v[76:77], v[72:75], off
	v_lshlrev_b32_e32 v78, 16, v224
	v_and_b32_e32 v79, 0xffff0000, v224
	v_lshlrev_b32_e32 v72, 16, v222
	v_and_b32_e32 v73, 0xffff0000, v222
	v_lshlrev_b32_e32 v80, 16, v225
	v_and_b32_e32 v81, 0xffff0000, v225
	v_lshlrev_b32_e32 v74, 16, v223
	v_and_b32_e32 v75, 0xffff0000, v223
	v_pk_fma_f32 v[68:69], v[68:69], v[132:133], v[72:73]
	v_pk_fma_f32 v[72:73], v[66:67], v[130:131], v[80:81]
	v_pk_fma_f32 v[66:67], v[64:65], v[128:129], v[78:79]
	v_pk_fma_f32 v[70:71], v[70:71], v[134:135], v[74:75]
	v_cvt_pk_bf16_f32 v64, v68, v69
	s_nop 0
	v_cvt_pk_bf16_f32 v65, v70, v71
	v_cvt_pk_bf16_f32 v66, v66, v67
	v_cvt_pk_bf16_f32 v67, v72, v73
	global_store_dwordx4 v[76:77], v[64:67], off offset:256
	s_mov_b64 s[14:15], 0xb0000
	v_lshl_add_u64 v[226:227], v[158:159], 0, s[58:59]
	v_lshl_add_u64 v[228:229], v[158:159], 0, s[14:15]
	v_lshl_add_u64 v[204:205], v[156:157], 0, v[226:227]
	v_lshl_add_u64 v[222:223], v[156:157], 0, v[228:229]
	global_load_dwordx4 v[200:203], v[204:205], off
	s_nop 0
	global_load_dwordx4 v[204:207], v[204:205], off offset:256
	s_nop 0
	global_load_dwordx4 v[208:211], v[222:223], off
	s_nop 0
	global_load_dwordx4 v[222:225], v[222:223], off offset:256
	s_waitcnt vmcnt(8)
; __device__ __forceinline__ float bf_lo(unsigned u) { return __uint_as_float(u << 16); }
; __device__ __forceinline__ float bf_hi(unsigned u) { return __uint_as_float(u & 0xffff0000u); }
; #define PG8_BAR __builtin_amdgcn_s_barrier()
; __device__ __forceinline__ u32x4 pack8(const f32x4 a, const f32x4 b) { u32x4 w; w.x = cvt_pk_bf16(a[0], a[1]); w.y = cvt_pk_bf16(a[2], a[3]); w.z = cvt_pk_bf16(b[0], b[1]); w.w = cvt_pk_bf16(b[2], b[3]); return w; }
; template <int NT, class Epi>
; __device__ __forceinline__ void gemm_phase(LAS unsigned char* lds, const int K, const Sched& S, const Epi& E, const int wave_s) {
;     ...
;         if (wr == 0) PG8_BAR;
;         const bool keep = E(acc, cur, wr, wc, fr, fq);
;         __builtin_amdgcn_s_waitcnt(0x0F70);
;         if (!has_next) break;
;         if (!keep) {
; #pragma unroll
;             for (int a = 0; a < 2; ++a)
; #pragma unroll
;                 for (int b = 0; b < 2; ++b)
; #pragma unroll
;                     for (int m = 0; m < 4; ++m)
; #pragma unroll
;                         for (int n = 0; n < 2; ++n) acc[a][b][m][n] = (f32x4){0.f, 0.f, 0.f, 0.f};
;         }
;         cur = nxt; cA = nA; cB = nB; ++ui;
;         if (wr == 1) PG8_BAR;
;     __device__ __forceinline__ bool operator()(f32x4 (&acc)[2][2][4][2], const Unit& u, int wr, int wc, int fr, int fq) const {
;     ...
; #pragma unroll
;         for (int b4 = 0; b4 < 4; ++b4) {
;             const int ai = b4 >> 1, mh = (b4 & 1) * 2;
;             u32x4 xq[2][2];
; #pragma unroll
;             for (int mm = 0; mm < 2; ++mm)
; #pragma unroll
;                 for (int bj = 0; bj < 2; ++bj) xq[mm][bj] = *(const u32x4*)(xb + (size_t)(row0 + ai * 128 + (mh + mm) * 16) * D + c0 + bj * 128);
;             __builtin_amdgcn_sched_barrier(0);
; #pragma unroll
;             for (int mm = 0; mm < 2; ++mm)
; #pragma unroll
;                 for (int bj = 0; bj < 2; ++bj)
;                 { const u32x4 q = xq[mm][bj]; const f32x4 x0 = (f32x4){bf_lo(q.x), bf_hi(q.x), bf_lo(q.y), bf_hi(q.y)}, x1 = (f32x4){bf_lo(q.z), bf_hi(q.z), bf_lo(q.w), bf_hi(q.w)};
;                     *(u32x4*)(xb + (size_t)(row0 + ai * 128 + (mh + mm) * 16) * D + c0 + bj * 128) = pack8(x0 + gv[bj][0] * acc[ai][bj][mh + mm][0], x1 + gv[bj][1] * acc[ai][bj][mh + mm][1]); }
;             __builtin_amdgcn_sched_barrier(0);
;         }
	v_lshlrev_b32_e32 v84, 16, v230
	v_and_b32_e32 v85, 0xffff0000, v230
	v_lshlrev_b32_e32 v230, 16, v231
	v_and_b32_e32 v231, 0xffff0000, v231
	v_lshlrev_b32_e32 v86, 16, v232
	v_and_b32_e32 v87, 0xffff0000, v232
	v_lshlrev_b32_e32 v232, 16, v233
	v_and_b32_e32 v233, 0xffff0000, v233
	v_pk_fma_f32 v[60:61], v[60:61], v[140:141], v[84:85]
	v_pk_fma_f32 v[62:63], v[62:63], v[142:143], v[230:231]
	v_pk_fma_f32 v[230:231], v[58:59], v[138:139], v[232:233]
	v_pk_fma_f32 v[58:59], v[56:57], v[136:137], v[86:87]
	v_cvt_pk_bf16_f32 v56, v60, v61
	v_lshl_add_u64 v[60:61], s[6:7], 0, v[242:243]
	v_cvt_pk_bf16_f32 v57, v62, v63
	v_cvt_pk_bf16_f32 v58, v58, v59
	v_cvt_pk_bf16_f32 v59, v230, v231
	v_lshl_add_u64 v[60:61], v[60:61], 0, v[154:155]
	global_store_dwordx4 v[60:61], v[56:59], off
	v_lshlrev_b32_e32 v62, 16, v236
	v_and_b32_e32 v63, 0xffff0000, v236
	v_lshlrev_b32_e32 v56, 16, v234
	v_and_b32_e32 v57, 0xffff0000, v234
	v_lshlrev_b32_e32 v58, 16, v235
	v_and_b32_e32 v59, 0xffff0000, v235
	v_lshlrev_b32_e32 v230, 16, v237
	v_and_b32_e32 v231, 0xffff0000, v237
	v_pk_fma_f32 v[54:55], v[54:55], v[134:135], v[58:59]
	v_pk_fma_f32 v[52:53], v[52:53], v[132:133], v[56:57]
	v_pk_fma_f32 v[56:57], v[50:51], v[130:131], v[230:231]
	v_pk_fma_f32 v[50:51], v[48:49], v[128:129], v[62:63]
	v_cvt_pk_bf16_f32 v48, v52, v53
	v_cvt_pk_bf16_f32 v49, v54, v55
	v_lshlrev_b32_e32 v52, 16, v240
	v_cvt_pk_bf16_f32 v50, v50, v51
	v_cvt_pk_bf16_f32 v51, v56, v57
	global_store_dwordx4 v[60:61], v[48:51], off offset:256
	v_and_b32_e32 v53, 0xffff0000, v240
	v_lshlrev_b32_e32 v54, 16, v241
	v_lshlrev_b32_e32 v48, 16, v238
	v_and_b32_e32 v49, 0xffff0000, v238
	v_and_b32_e32 v55, 0xffff0000, v241
	v_pk_fma_f32 v[44:45], v[44:45], v[140:141], v[48:49]
	v_lshlrev_b32_e32 v50, 16, v239
	v_and_b32_e32 v51, 0xffff0000, v239
	v_pk_fma_f32 v[48:49], v[42:43], v[138:139], v[54:55]
	v_pk_fma_f32 v[42:43], v[40:41], v[136:137], v[52:53]
	v_cvt_pk_bf16_f32 v40, v44, v45
	v_lshl_add_u64 v[44:45], s[6:7], 0, v[250:251]
	v_pk_fma_f32 v[46:47], v[46:47], v[142:143], v[50:51]
	v_lshl_add_u64 v[44:45], v[44:45], 0, v[154:155]
	v_cvt_pk_bf16_f32 v41, v46, v47
	v_cvt_pk_bf16_f32 v42, v42, v43
	v_cvt_pk_bf16_f32 v43, v48, v49
	global_store_dwordx4 v[44:45], v[40:43], off
	v_lshlrev_b32_e32 v46, 16, v248
	v_and_b32_e32 v47, 0xffff0000, v248
	v_lshlrev_b32_e32 v40, 16, v246
	v_and_b32_e32 v41, 0xffff0000, v246
	v_lshlrev_b32_e32 v48, 16, v249
	v_and_b32_e32 v49, 0xffff0000, v249
	v_lshlrev_b32_e32 v42, 16, v247
	v_and_b32_e32 v43, 0xffff0000, v247
	v_pk_fma_f32 v[36:37], v[36:37], v[132:133], v[40:41]
	v_pk_fma_f32 v[40:41], v[34:35], v[130:131], v[48:49]
	v_pk_fma_f32 v[34:35], v[32:33], v[128:129], v[46:47]
	v_pk_fma_f32 v[38:39], v[38:39], v[134:135], v[42:43]
	v_cvt_pk_bf16_f32 v32, v36, v37
	s_nop 0
	v_cvt_pk_bf16_f32 v33, v38, v39
	v_cvt_pk_bf16_f32 v34, v34, v35
	v_cvt_pk_bf16_f32 v35, v40, v41
	global_store_dwordx4 v[44:45], v[32:35], off offset:256
	s_waitcnt vmcnt(4)
	v_lshlrev_b32_e32 v52, 16, v200
	v_and_b32_e32 v53, 0xffff0000, v200
	v_lshlrev_b32_e32 v200, 16, v201
	v_and_b32_e32 v201, 0xffff0000, v201
	v_lshlrev_b32_e32 v54, 16, v202
	v_and_b32_e32 v55, 0xffff0000, v202
	v_lshlrev_b32_e32 v202, 16, v203
	v_and_b32_e32 v203, 0xffff0000, v203
	v_pk_fma_f32 v[28:29], v[28:29], v[140:141], v[52:53]
	v_pk_fma_f32 v[30:31], v[30:31], v[142:143], v[200:201]
	v_pk_fma_f32 v[200:201], v[26:27], v[138:139], v[202:203]
	v_pk_fma_f32 v[26:27], v[24:25], v[136:137], v[54:55]
	v_cvt_pk_bf16_f32 v24, v28, v29
	v_lshl_add_u64 v[28:29], s[6:7], 0, v[226:227]
	v_cvt_pk_bf16_f32 v25, v30, v31
	v_cvt_pk_bf16_f32 v26, v26, v27
	v_cvt_pk_bf16_f32 v27, v200, v201
	v_lshl_add_u64 v[28:29], v[28:29], 0, v[154:155]
	global_store_dwordx4 v[28:29], v[24:27], off
	v_lshlrev_b32_e32 v30, 16, v206
	v_and_b32_e32 v31, 0xffff0000, v206
	v_lshlrev_b32_e32 v24, 16, v204
	v_and_b32_e32 v25, 0xffff0000, v204
	v_lshlrev_b32_e32 v26, 16, v205
	v_and_b32_e32 v27, 0xffff0000, v205
	v_lshlrev_b32_e32 v200, 16, v207
	v_and_b32_e32 v201, 0xffff0000, v207
	v_pk_fma_f32 v[22:23], v[22:23], v[134:135], v[26:27]
	v_pk_fma_f32 v[20:21], v[20:21], v[132:133], v[24:25]
	v_pk_fma_f32 v[24:25], v[18:19], v[130:131], v[200:201]
	v_pk_fma_f32 v[18:19], v[16:17], v[128:129], v[30:31]
	v_cvt_pk_bf16_f32 v16, v20, v21
	v_cvt_pk_bf16_f32 v17, v22, v23
	v_lshlrev_b32_e32 v20, 16, v210
	v_cvt_pk_bf16_f32 v18, v18, v19
	v_cvt_pk_bf16_f32 v19, v24, v25
	global_store_dwordx4 v[28:29], v[16:19], off offset:256
	v_and_b32_e32 v21, 0xffff0000, v210
	v_lshlrev_b32_e32 v22, 16, v211
	v_lshlrev_b32_e32 v16, 16, v208
	v_and_b32_e32 v17, 0xffff0000, v208
	v_and_b32_e32 v23, 0xffff0000, v211
	v_pk_fma_f32 v[12:13], v[12:13], v[140:141], v[16:17]
	v_lshlrev_b32_e32 v18, 16, v209
	v_and_b32_e32 v19, 0xffff0000, v209
	v_pk_fma_f32 v[16:17], v[10:11], v[138:139], v[22:23]
	v_pk_fma_f32 v[10:11], v[8:9], v[136:137], v[20:21]
	v_cvt_pk_bf16_f32 v8, v12, v13
	v_lshl_add_u64 v[12:13], s[6:7], 0, v[228:229]
	v_pk_fma_f32 v[14:15], v[14:15], v[142:143], v[18:19]
	v_lshl_add_u64 v[12:13], v[12:13], 0, v[154:155]
	v_cvt_pk_bf16_f32 v9, v14, v15
	v_cvt_pk_bf16_f32 v10, v10, v11
	v_cvt_pk_bf16_f32 v11, v16, v17
	global_store_dwordx4 v[12:13], v[8:11], off
	v_lshlrev_b32_e32 v14, 16, v224
	v_and_b32_e32 v15, 0xffff0000, v224
	v_lshlrev_b32_e32 v8, 16, v222
	v_and_b32_e32 v9, 0xffff0000, v222
	v_lshlrev_b32_e32 v16, 16, v225
	v_and_b32_e32 v17, 0xffff0000, v225
	v_lshlrev_b32_e32 v10, 16, v223
	v_and_b32_e32 v11, 0xffff0000, v223
	v_pk_fma_f32 v[4:5], v[4:5], v[132:133], v[8:9]
	v_pk_fma_f32 v[8:9], v[2:3], v[130:131], v[16:17]
	v_pk_fma_f32 v[2:3], v[0:1], v[128:129], v[14:15]
	v_pk_fma_f32 v[6:7], v[6:7], v[134:135], v[10:11]
	v_cvt_pk_bf16_f32 v0, v4, v5
	s_nop 0
	v_cvt_pk_bf16_f32 v1, v6, v7
	v_cvt_pk_bf16_f32 v2, v2, v3
	v_cvt_pk_bf16_f32 v3, v8, v9
	global_store_dwordx4 v[12:13], v[0:3], off offset:256
	v_readlane_b32 s40, v255, 38
	s_andn2_b64 vcc, exec, s[38:39]
	s_mov_b64 s[28:29], -1
	v_readlane_b32 s97, v255, 18
	v_readlane_b32 s41, v255, 39
	s_cbranch_vccnz .LBB0_109
	s_andn2_b64 vcc, exec, s[8:9]
	s_cbranch_vccnz .LBB0_108
	s_barrier
	s_branch .LBB0_108

; template <int NT, class Epi>
; __device__ __forceinline__ void gemm_phase(LAS unsigned char* lds, const int K, const Sched& S, const Epi& E, const int wave_s) {
;     ...
;         const bool keep = E(acc, cur, wr, wc, fr, fq);
;         __builtin_amdgcn_s_waitcnt(0x0F70);
;         if (!has_next) break;
;         if (!keep) {
; #pragma unroll
;             for (int a = 0; a < 2; ++a)
; #pragma unroll
;                 for (int b = 0; b < 2; ++b)
; #pragma unroll
;                     for (int m = 0; m < 4; ++m)
; #pragma unroll
;                         for (int n = 0; n < 2; ++n) acc[a][b][m][n] = (f32x4){0.f, 0.f, 0.f, 0.f};
;         }
.LBB0_327:
	s_and_b64 vcc, exec, s[38:39]
	s_mov_b64 s[8:9], -1
	s_mov_b64 s[38:39], 0x800
	s_cbranch_vccnz .LBB0_211
	s_andn2_b64 vcc, exec, s[12:13]
	s_cbranch_vccnz .LBB0_330
	v_mov_b32_e32 v0, 0
	v_mov_b32_e32 v1, v0
	v_mov_b32_e32 v2, v0
	v_mov_b32_e32 v3, v0
	v_mov_b32_e32 v4, v0
	v_mov_b32_e32 v5, v0
	v_mov_b32_e32 v6, v0
	v_mov_b32_e32 v7, v0
	v_mov_b32_e32 v8, v0
	v_mov_b32_e32 v9, v0
	v_mov_b32_e32 v10, v0
	v_mov_b32_e32 v11, v0
	v_mov_b32_e32 v12, v0
	v_mov_b32_e32 v13, v0
	v_mov_b32_e32 v14, v0
	v_mov_b32_e32 v15, v0
	v_mov_b32_e32 v16, v0
	v_mov_b32_e32 v17, v0
	v_mov_b32_e32 v18, v0
	v_mov_b32_e32 v19, v0
	v_mov_b32_e32 v20, v0
	v_mov_b32_e32 v21, v0
	v_mov_b32_e32 v22, v0
	v_mov_b32_e32 v23, v0
	v_mov_b32_e32 v24, v0
	v_mov_b32_e32 v25, v0
	v_mov_b32_e32 v26, v0
	v_mov_b32_e32 v27, v0
	v_mov_b32_e32 v28, v0
	v_mov_b32_e32 v29, v0
	v_mov_b32_e32 v30, v0
	v_mov_b32_e32 v31, v0
	v_mov_b32_e32 v32, v0
	v_mov_b32_e32 v33, v0
	v_mov_b32_e32 v34, v0
	v_mov_b32_e32 v35, v0
	v_mov_b32_e32 v36, v0
	v_mov_b32_e32 v37, v0
	v_mov_b32_e32 v38, v0
	v_mov_b32_e32 v39, v0
	v_mov_b32_e32 v40, v0
	v_mov_b32_e32 v41, v0
	v_mov_b32_e32 v42, v0
	v_mov_b32_e32 v43, v0
	v_mov_b32_e32 v44, v0
	v_mov_b32_e32 v45, v0
	v_mov_b32_e32 v46, v0
	v_mov_b32_e32 v47, v0
	v_mov_b32_e32 v48, v0
	v_mov_b32_e32 v49, v0
	v_mov_b32_e32 v50, v0
	v_mov_b32_e32 v51, v0
	v_mov_b32_e32 v52, v0
	v_mov_b32_e32 v53, v0
	v_mov_b32_e32 v54, v0
	v_mov_b32_e32 v55, v0
	v_mov_b32_e32 v56, v0
	v_mov_b32_e32 v57, v0
	v_mov_b32_e32 v58, v0
	v_mov_b32_e32 v59, v0
	v_mov_b32_e32 v60, v0
	v_mov_b32_e32 v61, v0
	v_mov_b32_e32 v62, v0
	v_mov_b32_e32 v63, v0
	v_mov_b32_e32 v64, v0
	v_mov_b32_e32 v65, v0
	v_mov_b32_e32 v66, v0
	v_mov_b32_e32 v67, v0
	v_mov_b32_e32 v68, v0
	v_mov_b32_e32 v69, v0
	v_mov_b32_e32 v70, v0
	v_mov_b32_e32 v71, v0
	v_mov_b32_e32 v72, v0
	v_mov_b32_e32 v73, v0
	v_mov_b32_e32 v74, v0
	v_mov_b32_e32 v75, v0
	v_mov_b32_e32 v76, v0
	v_mov_b32_e32 v77, v0
	v_mov_b32_e32 v78, v0
	v_mov_b32_e32 v79, v0
	v_mov_b32_e32 v80, v0
	v_mov_b32_e32 v81, v0
	v_mov_b32_e32 v82, v0
	v_mov_b32_e32 v83, v0
	v_mov_b32_e32 v84, v0
	v_mov_b32_e32 v85, v0
	v_mov_b32_e32 v86, v0
	v_mov_b32_e32 v87, v0
	v_mov_b32_e32 v88, v0
	v_mov_b32_e32 v89, v0
	v_mov_b32_e32 v90, v0
	v_mov_b32_e32 v91, v0
	v_mov_b32_e32 v92, v0
	v_mov_b32_e32 v93, v0
	v_mov_b32_e32 v94, v0
	v_mov_b32_e32 v95, v0
	v_mov_b32_e32 v96, v0
	v_mov_b32_e32 v97, v0
	v_mov_b32_e32 v98, v0
	v_mov_b32_e32 v99, v0
	v_mov_b32_e32 v100, v0
	v_mov_b32_e32 v101, v0
	v_mov_b32_e32 v102, v0
	v_mov_b32_e32 v103, v0
	v_mov_b32_e32 v104, v0
	v_mov_b32_e32 v105, v0
	v_mov_b32_e32 v106, v0
	v_mov_b32_e32 v107, v0
	v_mov_b32_e32 v108, v0
	v_mov_b32_e32 v109, v0
	v_mov_b32_e32 v110, v0
	v_mov_b32_e32 v111, v0
	v_mov_b32_e32 v112, v0
	v_mov_b32_e32 v113, v0
	v_mov_b32_e32 v114, v0
	v_mov_b32_e32 v115, v0
	v_mov_b32_e32 v116, v0
	v_mov_b32_e32 v117, v0
	v_mov_b32_e32 v118, v0
	v_mov_b32_e32 v119, v0
	v_mov_b32_e32 v120, v0
	v_mov_b32_e32 v121, v0
	v_mov_b32_e32 v122, v0
	v_mov_b32_e32 v123, v0
	v_mov_b32_e32 v124, v0
	v_mov_b32_e32 v125, v0
	v_mov_b32_e32 v126, v0
	v_mov_b32_e32 v127, v0

; #define PG8_BAR __builtin_amdgcn_s_barrier()
; template <int NT, class Epi>
; __device__ __forceinline__ void gemm_phase(LAS unsigned char* lds, const int K, const Sched& S, const Epi& E, const int wave_s) {
;     ...
;         if (wr == 0) PG8_BAR;
;         const bool keep = E(acc, cur, wr, wc, fr, fq);
;         __builtin_amdgcn_s_waitcnt(0x0F70);
;         if (!has_next) break;
;         if (!keep) {
; #pragma unroll
;             for (int a = 0; a < 2; ++a)
; #pragma unroll
;                 for (int b = 0; b < 2; ++b)
; #pragma unroll
;                     for (int m = 0; m < 4; ++m)
; #pragma unroll
;                         for (int n = 0; n < 2; ++n) acc[a][b][m][n] = (f32x4){0.f, 0.f, 0.f, 0.f};
;         }
;         cur = nxt; cA = nA; cB = nB; ++ui;
;         if (wr == 1) PG8_BAR;
.LBB0_432:
	s_andn2_b64 vcc, exec, s[40:41]
	v_readlane_b32 s40, v255, 38
	s_mov_b64 s[0:1], -1
	v_readlane_b32 s41, v255, 39
	s_cbranch_vccnz .LBB0_389
	s_andn2_b64 vcc, exec, s[78:79]
	s_cbranch_vccnz .LBB0_388
	s_barrier
	s_branch .LBB0_388

; __device__ __forceinline__ unsigned cvt_pk_bf16(float lo, float hi) { unsigned r; asm volatile("v_cvt_pk_bf16_f32 %0, %1, %2" : "=v"(r) : "v"(lo), "v"(hi)); return r; }
; __device__ __forceinline__ float bf_lo(unsigned u) { return __uint_as_float(u << 16); }
; __device__ __forceinline__ float bf_hi(unsigned u) { return __uint_as_float(u & 0xffff0000u); }
; __global__ void __launch_bounds__(512, 2) fwd_kernel(const Args a) {
;     ...
;                 if (fastlat) {
;                     u32x2 nq[8];
;                     { const u32x2* xq0 = (const u32x2*)(XBb + (size_t)(m_beg < ML ? m_beg : 0) * D);
; #pragma unroll
;                         for (int j = 0; j < 8; ++j) nq[j] = xq0[64 * j + lane]; }
;                     for (int m = m_beg; m < m_end; m += m_str) {
;                         const float* shp = ada + (m >> 13) * 12288 + so; const float* scp = shp + 2048;
;                         f32x4 v[8]; float ss = 0.f;
; #pragma unroll
;                         for (int j = 0; j < 8; ++j) { const u32x2 q = nq[j]; v[j] = (f32x4){bf_lo(q.x), bf_hi(q.x), bf_lo(q.y), bf_hi(q.y)}; }
;                         if (m + m_str < m_end) { const u32x2* xqn = (const u32x2*)(XBb + (size_t)(m + m_str) * D);
; #pragma unroll
;                             for (int j = 0; j < 8; ++j) nq[j] = xqn[64 * j + lane]; }
;                         __builtin_amdgcn_sched_barrier(0);
; #pragma unroll
;                         for (int j = 0; j < 8; ++j) ss += (v[j].x * v[j].x + v[j].y * v[j].y) + (v[j].z * v[j].z + v[j].w * v[j].w);
;                         const float rs = rsqrtf(wave_sum(ss, lane) * (1.0f / D) + EPS);
;                         u32x2* o8 = (u32x2*)(Hb + (size_t)m * D) + lane;
; #pragma unroll
;                         for (int j = 0; j < 8; ++j) { const f32x4 g = ((const f32x4*)ng)[64 * j + lane], sc = ((const f32x4*)scp)[64 * j + lane], sh = ((const f32x4*)shp)[64 * j + lane];
;                             const f32x4 y = (v[j] * rs) * g * (sc + 1.0f) + sh; u32x2 w; w.x = cvt_pk_bf16(y.x, y.y); w.y = cvt_pk_bf16(y.z, y.w); o8[64 * j] = w; }
;                     }
.LBB0_473:
	s_mov_b64 s[82:83], s[56:57]
	v_readlane_b32 s42, v255, 26
	v_readlane_b32 s54, v255, 28
	v_readlane_b32 s56, v255, 30
	v_readlane_b32 s58, v255, 32
	v_readlane_b32 s84, v255, 34
	v_readlane_b32 s90, v255, 36
	v_readlane_b32 s40, v255, 38
	v_readlane_b32 s22, v255, 40
	v_readlane_b32 s16, v255, 42
	s_andn2_b64 vcc, exec, s[30:31]
	s_mov_b32 s64, s52
	v_readlane_b32 s43, v255, 27
	v_readlane_b32 s55, v255, 29
	v_readlane_b32 s57, v255, 31
	v_readlane_b32 s59, v255, 33
	v_readlane_b32 s85, v255, 35
	v_readlane_b32 s91, v255, 37
	v_readlane_b32 s41, v255, 39
	v_readlane_b32 s23, v255, 41
	v_readlane_b32 s17, v255, 43
	s_movk_i32 s52, 0xfeff
	s_mov_b64 s[38:39], 0x800
	s_cbranch_vccnz .LBB0_479
	s_cmp_ge_i32 s10, s2
	s_cbranch_scc1 .LBB0_479
	s_cmpk_lt_i32 s10, 0x4000
	s_cselect_b32 s0, s10, 0
	s_ashr_i32 s1, s0, 31
	s_lshl_b64 s[0:1], s[0:1], 12
	s_add_u32 s0, s6, s0
	s_addc_u32 s1, s7, s1
	v_lshlrev_b32_e32 v176, 3, v188
	global_load_dwordx2 v[46:47], v176, s[0:1]
	global_load_dwordx2 v[44:45], v176, s[0:1] offset:512
	global_load_dwordx2 v[42:43], v176, s[0:1] offset:1024
	global_load_dwordx2 v[40:41], v176, s[0:1] offset:1536
	global_load_dwordx2 v[38:39], v176, s[0:1] offset:2048
	global_load_dwordx2 v[36:37], v176, s[0:1] offset:2560
	global_load_dwordx2 v[34:35], v176, s[0:1] offset:3072
	global_load_dwordx2 v[66:67], v176, s[0:1] offset:3584
	s_lshl_b32 s0, s9, 2
	v_readlane_b32 s1, v255, 44
	s_add_u32 s4, s1, s0
	v_readlane_b32 s0, v255, 45
	s_addc_u32 s20, s0, 0
	s_ashr_i32 s11, s10, 31
	s_lshl_b64 s[0:1], s[10:11], 12
	v_readlane_b32 s9, v254, 54
	v_or_b32_e32 v10, 0x100, v188
	v_or_b32_e32 v12, 0x140, v188
	v_or_b32_e32 v14, 0x180, v188
	v_or_b32_e32 v16, 0x1c0, v188
	s_add_u32 s0, s9, s0
	v_readlane_b32 s9, v254, 55
	v_or_b32_e32 v4, 64, v188
	v_or_b32_e32 v6, 0x80, v188
	v_or_b32_e32 v8, 0xc0, v188
	v_lshlrev_b32_e32 v2, 2, v188
	v_lshlrev_b32_e32 v0, 4, v188
	v_mov_b32_e32 v1, v177
	v_mov_b32_e32 v19, v177
	v_mov_b32_e32 v21, v177
	v_mov_b32_e32 v23, v177
	v_mov_b32_e32 v25, v177
	v_lshlrev_b32_e32 v18, 4, v10
	v_lshlrev_b32_e32 v20, 4, v12
	v_lshlrev_b32_e32 v22, 4, v14
	v_lshlrev_b32_e32 v24, 4, v16
	s_addc_u32 s1, s9, s1
	s_ashr_i32 s9, s8, 31
	v_lshlrev_b32_e32 v68, 4, v188
	v_xor_b32_e32 v69, 4, v2
	v_xor_b32_e32 v70, 8, v2
	v_xor_b32_e32 v71, 16, v2
	v_xor_b32_e32 v72, 32, v2
	v_xor_b32_e32 v73, 64, v2
	v_xor_b32_e32 v74, 0x80, v2
	v_lshl_add_u64 v[0:1], s[12:13], 0, v[0:1]
	v_lshl_add_u64 v[2:3], s[6:7], 0, v[176:177]
	v_lshlrev_b32_e32 v75, 4, v4
	v_lshlrev_b32_e32 v76, 4, v6
	v_lshlrev_b32_e32 v77, 4, v8
	v_lshlrev_b32_e32 v78, 4, v10
	v_lshlrev_b32_e32 v79, 4, v12
	v_lshlrev_b32_e32 v80, 4, v14
	v_lshlrev_b32_e32 v81, 4, v16
	v_lshl_add_u64 v[4:5], s[12:13], 0, v[18:19]
	v_lshl_add_u64 v[6:7], s[12:13], 0, v[20:21]
	v_lshl_add_u64 v[8:9], s[12:13], 0, v[22:23]
	v_lshl_add_u64 v[10:11], s[12:13], 0, v[24:25]
	v_lshl_add_u64 v[12:13], s[0:1], 0, v[176:177]
	s_lshl_b64 s[0:1], s[8:9], 12
	s_waitcnt vmcnt(0)
	v_mov_b64_e32 v[14:15], v[46:47]
	v_mov_b64_e32 v[16:17], v[44:45]
	v_mov_b64_e32 v[18:19], v[42:43]
	v_mov_b64_e32 v[20:21], v[40:41]
	v_mov_b64_e32 v[22:23], v[38:39]
	v_mov_b64_e32 v[24:25], v[36:37]
	v_mov_b64_e32 v[26:27], v[34:35]
	v_mov_b64_e32 v[28:29], v[66:67]
	s_mov_b32 s9, -1
	s_branch .LBB0_477
.LBB0_477:
	s_ashr_i32 s13, s10, 13
	s_cmp_eq_u32 s13, s9
	s_cbranch_scc1 .Lfl_coef_ok
	s_mov_b32 s9, s13
	s_mul_i32 s14, s13, 0x3000
	s_ashr_i32 s15, s14, 31
	s_lshl_b64 s[14:15], s[14:15], 2
	s_add_u32 s14, s4, s14
	s_addc_u32 s15, s20, s15
	s_add_u32 s24, s14, 0x2000
	s_addc_u32 s25, s15, 0
	global_load_dwordx4 v[96:99], v[0:1], off
	global_load_dwordx4 v[100:103], v[0:1], off offset:1024
	global_load_dwordx4 v[104:107], v[0:1], off offset:2048
	global_load_dwordx4 v[108:111], v[0:1], off offset:3072
	global_load_dwordx4 v[112:115], v[4:5], off
	global_load_dwordx4 v[116:119], v[6:7], off
	global_load_dwordx4 v[120:123], v[8:9], off
	global_load_dwordx4 v[124:127], v[10:11], off
	global_load_dwordx4 v[128:131], v68, s[24:25]
	global_load_dwordx4 v[132:135], v75, s[24:25]
	global_load_dwordx4 v[136:139], v76, s[24:25]
	global_load_dwordx4 v[140:143], v77, s[24:25]
	global_load_dwordx4 v[144:147], v78, s[24:25]
	global_load_dwordx4 v[148:151], v79, s[24:25]
	global_load_dwordx4 v[152:155], v80, s[24:25]
	global_load_dwordx4 v[156:159], v81, s[24:25]
	global_load_dwordx4 v[190:193], v68, s[14:15]
	global_load_dwordx4 v[194:197], v68, s[14:15] offset:1024
	global_load_dwordx4 v[198:201], v68, s[14:15] offset:2048
	global_load_dwordx4 v[202:205], v68, s[14:15] offset:3072
	global_load_dwordx4 v[222:225], v78, s[14:15]
	global_load_dwordx4 v[226:229], v79, s[14:15]
	global_load_dwordx4 v[230:233], v80, s[14:15]
	global_load_dwordx4 v[234:237], v81, s[14:15]
	s_waitcnt vmcnt(0)
	v_pk_add_f32 v[128:129], v[128:129], 1.0 op_sel_hi:[1,0]
	v_pk_add_f32 v[130:131], v[130:131], 1.0 op_sel_hi:[1,0]
	v_pk_add_f32 v[132:133], v[132:133], 1.0 op_sel_hi:[1,0]
	v_pk_add_f32 v[134:135], v[134:135], 1.0 op_sel_hi:[1,0]
	v_pk_add_f32 v[136:137], v[136:137], 1.0 op_sel_hi:[1,0]
	v_pk_add_f32 v[138:139], v[138:139], 1.0 op_sel_hi:[1,0]
	v_pk_add_f32 v[140:141], v[140:141], 1.0 op_sel_hi:[1,0]
	v_pk_add_f32 v[142:143], v[142:143], 1.0 op_sel_hi:[1,0]
	v_pk_add_f32 v[144:145], v[144:145], 1.0 op_sel_hi:[1,0]
	v_pk_add_f32 v[146:147], v[146:147], 1.0 op_sel_hi:[1,0]
	v_pk_add_f32 v[148:149], v[148:149], 1.0 op_sel_hi:[1,0]
	v_pk_add_f32 v[150:151], v[150:151], 1.0 op_sel_hi:[1,0]
	v_pk_add_f32 v[152:153], v[152:153], 1.0 op_sel_hi:[1,0]
	v_pk_add_f32 v[154:155], v[154:155], 1.0 op_sel_hi:[1,0]
	v_pk_add_f32 v[156:157], v[156:157], 1.0 op_sel_hi:[1,0]
	v_pk_add_f32 v[158:159], v[158:159], 1.0 op_sel_hi:[1,0]
; __device__ __forceinline__ float bf_lo(unsigned u) { return __uint_as_float(u << 16); }
; __device__ __forceinline__ float bf_hi(unsigned u) { return __uint_as_float(u & 0xffff0000u); }
; __global__ void __launch_bounds__(512, 2) fwd_kernel(const Args a) {
;     ...
;                         for (int j = 0; j < 8; ++j) { const u32x2 q = nq[j]; v[j] = (f32x4){bf_lo(q.x), bf_hi(q.x), bf_lo(q.y), bf_hi(q.y)}; }
;                         if (m + m_str < m_end) { const u32x2* xqn = (const u32x2*)(XBb + (size_t)(m + m_str) * D);
; #pragma unroll
;                             for (int j = 0; j < 8; ++j) nq[j] = xqn[64 * j + lane]; }
.Lfl_coef_ok:
	v_lshlrev_b32_e32 v14, 16, v46
	v_and_b32_e32 v15, 0xffff0000, v46
	v_lshlrev_b32_e32 v16, 16, v47
	v_and_b32_e32 v17, 0xffff0000, v47
	v_lshlrev_b32_e32 v18, 16, v44
	v_and_b32_e32 v19, 0xffff0000, v44
	v_lshlrev_b32_e32 v20, 16, v45
	v_and_b32_e32 v21, 0xffff0000, v45
	v_lshlrev_b32_e32 v22, 16, v42
	v_and_b32_e32 v23, 0xffff0000, v42
	v_lshlrev_b32_e32 v24, 16, v43
	v_and_b32_e32 v25, 0xffff0000, v43
	v_lshlrev_b32_e32 v26, 16, v40
	v_and_b32_e32 v27, 0xffff0000, v40
	v_lshlrev_b32_e32 v28, 16, v41
	v_and_b32_e32 v29, 0xffff0000, v41
	v_lshlrev_b32_e32 v48, 16, v38
	v_and_b32_e32 v49, 0xffff0000, v38
	v_lshlrev_b32_e32 v50, 16, v39
	v_and_b32_e32 v51, 0xffff0000, v39
	v_lshlrev_b32_e32 v52, 16, v36
	v_and_b32_e32 v53, 0xffff0000, v36
	v_lshlrev_b32_e32 v54, 16, v37
	v_and_b32_e32 v55, 0xffff0000, v37
	v_lshlrev_b32_e32 v56, 16, v34
	v_and_b32_e32 v57, 0xffff0000, v34
	v_lshlrev_b32_e32 v58, 16, v35
	v_and_b32_e32 v59, 0xffff0000, v35
	v_lshlrev_b32_e32 v60, 16, v66
	v_and_b32_e32 v61, 0xffff0000, v66
	v_lshlrev_b32_e32 v62, 16, v67
	v_and_b32_e32 v63, 0xffff0000, v67
	s_add_i32 s12, s10, s8
	s_cmp_ge_i32 s12, s2
	s_cbranch_scc1 .Lfl_nopf
	s_ashr_i32 s13, s12, 31
	s_lshl_b64 s[24:25], s[12:13], 12
	v_lshl_add_u64 v[82:83], v[2:3], 0, s[24:25]
	global_load_dwordx2 v[46:47], v[82:83], off
	global_load_dwordx2 v[44:45], v[82:83], off offset:512
	global_load_dwordx2 v[42:43], v[82:83], off offset:1024
	global_load_dwordx2 v[40:41], v[82:83], off offset:1536
	global_load_dwordx2 v[38:39], v[82:83], off offset:2048
	global_load_dwordx2 v[36:37], v[82:83], off offset:2560
	global_load_dwordx2 v[34:35], v[82:83], off offset:3072
	global_load_dwordx2 v[66:67], v[82:83], off offset:3584
; __device__ __forceinline__ unsigned cvt_pk_bf16(float lo, float hi) { unsigned r; asm volatile("v_cvt_pk_bf16_f32 %0, %1, %2" : "=v"(r) : "v"(lo), "v"(hi)); return r; }
; __global__ void __launch_bounds__(512, 2) fwd_kernel(const Args a) {
;     ...
;                         __builtin_amdgcn_sched_barrier(0);
; #pragma unroll
;                         for (int j = 0; j < 8; ++j) ss += (v[j].x * v[j].x + v[j].y * v[j].y) + (v[j].z * v[j].z + v[j].w * v[j].w);
;                         const float rs = rsqrtf(wave_sum(ss, lane) * (1.0f / D) + EPS);
;                         u32x2* o8 = (u32x2*)(Hb + (size_t)m * D) + lane;
; #pragma unroll
;                         for (int j = 0; j < 8; ++j) { const f32x4 g = ((const f32x4*)ng)[64 * j + lane], sc = ((const f32x4*)scp)[64 * j + lane], sh = ((const f32x4*)shp)[64 * j + lane];
;                             const f32x4 y = (v[j] * rs) * g * (sc + 1.0f) + sh; u32x2 w; w.x = cvt_pk_bf16(y.x, y.y); w.y = cvt_pk_bf16(y.z, y.w); o8[64 * j] = w; }
.Lfl_nopf:
	v_pk_mul_f32 v[206:207], v[14:15], v[14:15]
	v_pk_mul_f32 v[208:209], v[16:17], v[16:17]
	v_pk_fma_f32 v[206:207], v[18:19], v[18:19], v[206:207]
	v_pk_fma_f32 v[208:209], v[20:21], v[20:21], v[208:209]
	v_pk_fma_f32 v[206:207], v[22:23], v[22:23], v[206:207]
	v_pk_fma_f32 v[208:209], v[24:25], v[24:25], v[208:209]
	v_pk_fma_f32 v[206:207], v[26:27], v[26:27], v[206:207]
	v_pk_fma_f32 v[208:209], v[28:29], v[28:29], v[208:209]
	v_pk_fma_f32 v[206:207], v[48:49], v[48:49], v[206:207]
	v_pk_fma_f32 v[208:209], v[50:51], v[50:51], v[208:209]
	v_pk_fma_f32 v[206:207], v[52:53], v[52:53], v[206:207]
	v_pk_fma_f32 v[208:209], v[54:55], v[54:55], v[208:209]
	v_pk_fma_f32 v[206:207], v[56:57], v[56:57], v[206:207]
	v_pk_fma_f32 v[208:209], v[58:59], v[58:59], v[208:209]
	v_pk_fma_f32 v[206:207], v[60:61], v[60:61], v[206:207]
	v_pk_fma_f32 v[208:209], v[62:63], v[62:63], v[208:209]
	v_pk_add_f32 v[206:207], v[206:207], v[208:209]
	s_nop 0
	v_add_f32_e32 v210, v206, v207
	ds_bpermute_b32 v211, v69, v210
	s_waitcnt lgkmcnt(0)
	v_add_f32_e32 v210, v210, v211
	ds_bpermute_b32 v211, v70, v210
	s_waitcnt lgkmcnt(0)
	v_add_f32_e32 v210, v210, v211
	ds_bpermute_b32 v211, v71, v210
	s_waitcnt lgkmcnt(0)
	v_add_f32_e32 v210, v210, v211
	ds_bpermute_b32 v211, v72, v210
	s_waitcnt lgkmcnt(0)
	v_add_f32_e32 v210, v210, v211
	ds_bpermute_b32 v211, v73, v210
	s_waitcnt lgkmcnt(0)
	v_add_f32_e32 v210, v210, v211
	ds_bpermute_b32 v211, v74, v210
	s_waitcnt lgkmcnt(0)
	v_add_f32_e32 v210, v210, v211
	v_fmamk_f32 v210, v210, 0x3a000000, v216
	v_mul_f32_e32 v211, 0x4b800000, v210
	v_cmp_gt_f32_e32 vcc, s44, v210
	s_nop 1
	v_cndmask_b32_e32 v210, v210, v211, vcc
	v_rsq_f32_e32 v210, v210
	s_nop 0
	v_mul_f32_e32 v211, 0x45800000, v210
	v_cndmask_b32_e32 v210, v210, v211, vcc
	v_pk_mul_f32 v[206:207], v[210:211], v[14:15] op_sel_hi:[0,1]
	v_pk_mul_f32 v[208:209], v[210:211], v[16:17] op_sel_hi:[0,1]
	v_pk_mul_f32 v[206:207], v[96:97], v[206:207]
	v_pk_mul_f32 v[208:209], v[98:99], v[208:209]
	v_pk_fma_f32 v[206:207], v[128:129], v[206:207], v[190:191]
	v_pk_fma_f32 v[208:209], v[130:131], v[208:209], v[192:193]
	v_cvt_pk_bf16_f32 v84, v206, v207
	v_cvt_pk_bf16_f32 v85, v208, v209
	global_store_dwordx2 v[12:13], v[84:85], off offset:-3584
	v_pk_mul_f32 v[206:207], v[210:211], v[18:19] op_sel_hi:[0,1]
	v_pk_mul_f32 v[208:209], v[210:211], v[20:21] op_sel_hi:[0,1]
	v_pk_mul_f32 v[206:207], v[100:101], v[206:207]
	v_pk_mul_f32 v[208:209], v[102:103], v[208:209]
	v_pk_fma_f32 v[206:207], v[132:133], v[206:207], v[194:195]
	v_pk_fma_f32 v[208:209], v[134:135], v[208:209], v[196:197]
	v_cvt_pk_bf16_f32 v86, v206, v207
	v_cvt_pk_bf16_f32 v87, v208, v209
	global_store_dwordx2 v[12:13], v[86:87], off offset:-3072
	v_pk_mul_f32 v[206:207], v[210:211], v[22:23] op_sel_hi:[0,1]
	v_pk_mul_f32 v[208:209], v[210:211], v[24:25] op_sel_hi:[0,1]
	v_pk_mul_f32 v[206:207], v[104:105], v[206:207]
	v_pk_mul_f32 v[208:209], v[106:107], v[208:209]
	v_pk_fma_f32 v[206:207], v[136:137], v[206:207], v[198:199]
	v_pk_fma_f32 v[208:209], v[138:139], v[208:209], v[200:201]
	v_cvt_pk_bf16_f32 v88, v206, v207
	v_cvt_pk_bf16_f32 v89, v208, v209
	global_store_dwordx2 v[12:13], v[88:89], off offset:-2560
	v_pk_mul_f32 v[206:207], v[210:211], v[26:27] op_sel_hi:[0,1]
	v_pk_mul_f32 v[208:209], v[210:211], v[28:29] op_sel_hi:[0,1]
	v_pk_mul_f32 v[206:207], v[108:109], v[206:207]
	v_pk_mul_f32 v[208:209], v[110:111], v[208:209]
	v_pk_fma_f32 v[206:207], v[140:141], v[206:207], v[202:203]
	v_pk_fma_f32 v[208:209], v[142:143], v[208:209], v[204:205]
	v_cvt_pk_bf16_f32 v90, v206, v207
	v_cvt_pk_bf16_f32 v91, v208, v209
	global_store_dwordx2 v[12:13], v[90:91], off offset:-2048
	v_pk_mul_f32 v[206:207], v[210:211], v[48:49] op_sel_hi:[0,1]
	v_pk_mul_f32 v[208:209], v[210:211], v[50:51] op_sel_hi:[0,1]
	v_pk_mul_f32 v[206:207], v[112:113], v[206:207]
	v_pk_mul_f32 v[208:209], v[114:115], v[208:209]
	v_pk_fma_f32 v[206:207], v[144:145], v[206:207], v[222:223]
	v_pk_fma_f32 v[208:209], v[146:147], v[208:209], v[224:225]
	v_cvt_pk_bf16_f32 v92, v206, v207
	v_cvt_pk_bf16_f32 v93, v208, v209
	global_store_dwordx2 v[12:13], v[92:93], off offset:-1536
	v_pk_mul_f32 v[206:207], v[210:211], v[52:53] op_sel_hi:[0,1]
	v_pk_mul_f32 v[208:209], v[210:211], v[54:55] op_sel_hi:[0,1]
	v_pk_mul_f32 v[206:207], v[116:117], v[206:207]
	v_pk_mul_f32 v[208:209], v[118:119], v[208:209]
	v_pk_fma_f32 v[206:207], v[148:149], v[206:207], v[226:227]
	v_pk_fma_f32 v[208:209], v[150:151], v[208:209], v[228:229]
	v_cvt_pk_bf16_f32 v94, v206, v207
	v_cvt_pk_bf16_f32 v95, v208, v209
	global_store_dwordx2 v[12:13], v[94:95], off offset:-1024
	v_pk_mul_f32 v[206:207], v[210:211], v[56:57] op_sel_hi:[0,1]
	v_pk_mul_f32 v[208:209], v[210:211], v[58:59] op_sel_hi:[0,1]
	v_pk_mul_f32 v[206:207], v[120:121], v[206:207]
	v_pk_mul_f32 v[208:209], v[122:123], v[208:209]
	v_pk_fma_f32 v[206:207], v[152:153], v[206:207], v[230:231]
	v_pk_fma_f32 v[208:209], v[154:155], v[208:209], v[232:233]
	v_cvt_pk_bf16_f32 v64, v206, v207
	v_cvt_pk_bf16_f32 v65, v208, v209
	global_store_dwordx2 v[12:13], v[64:65], off offset:-512
	v_pk_mul_f32 v[206:207], v[210:211], v[60:61] op_sel_hi:[0,1]
	v_pk_mul_f32 v[208:209], v[210:211], v[62:63] op_sel_hi:[0,1]
	v_pk_mul_f32 v[206:207], v[124:125], v[206:207]
	v_pk_mul_f32 v[208:209], v[126:127], v[208:209]
	v_pk_fma_f32 v[206:207], v[156:157], v[206:207], v[234:235]
	v_pk_fma_f32 v[208:209], v[158:159], v[208:209], v[236:237]
	v_cvt_pk_bf16_f32 v32, v206, v207
	v_cvt_pk_bf16_f32 v33, v208, v209
	global_store_dwordx2 v[12:13], v[32:33], off
	v_lshl_add_u64 v[12:13], v[12:13], 0, s[0:1]
	s_cmp_ge_i32 s12, s2
	s_cbranch_scc1 .LBB0_479
	s_mov_b32 s10, s12
	s_waitcnt vmcnt(8)
	s_branch .LBB0_477
